# plus batched OUTPROJ acc-init, hoisted subln loads in attention epilogue, batched SSD ssq LDS reads
# speedup vs baseline: 1.0299x; 1.0044x over previous
; __device__ __forceinline__ void phase_attn(KP P, char* smem, const int wv) {
;     ...
;     if (cm == 0 && wave_valid) {
; #pragma unroll
;       for (int qt = 0; qt < 2; ++qt) {
;         float rl = 1.f / lrun[qt];
;         float ss = 0.f;
; #pragma unroll
;         for (int et = 0; et < 8; ++et) {
;           f32x4 o1 = *(const f32x4*)(sO + (rg * 32 + qt * 16 + fr) * A_LDO + et * 16 + fq * 4);
;           f32x4 o = oacc[qt][et] * rl - o1 * lam;
;           oacc[qt][et] = o;
;           ss += o[0] * o[0] + o[1] * o[1] + o[2] * o[2] + o[3] * o[3];
;         }
;         ss = xsum_16_32(ss);
;         float rstd = rsqrtf(ss * (1.f / 128.f) + EPS) * (1.f - LAMBDA_INIT);
;         bfu* dst = ao + (size_t)(qrow0 + rg * 32 + qt * 16 + fr) * 1024 + h * 128;
;         int fqe = fq;
;         asm volatile("" : "+v"(fqe));
; #pragma unroll
;         for (int et = 0; et < 8; ++et) {
;           int e0 = et * 16 + fqe * 4;
;           f32x4 sw = *(const f32x4*)(subln + e0);
;           uint2 pk;
;           pk.x = cvt_pk_bf16(oacc[qt][et][0] * rstd * sw[0], oacc[qt][et][1] * rstd * sw[1]);
;           pk.y = cvt_pk_bf16(oacc[qt][et][2] * rstd * sw[2], oacc[qt][et][3] * rstd * sw[3]);
;           *(uint2*)(dst + e0) = pk;
;         }
.LBB0_81:
	v_readlane_b32 s8, v241, 14
	v_readlane_b32 s9, v241, 15
	s_and_b64 s[6:7], s[8:9], s[6:7]
	s_andn2_b64 vcc, exec, s[6:7]
	s_waitcnt lgkmcnt(0)
	s_barrier
	s_cbranch_vccnz .LBB0_30
	v_div_scale_f32 v84, s[8:9], v83, v83, 1.0
	v_rcp_f32_e32 v85, v84
	v_add_u32_e32 v82, s62, v179
	s_lshl_b64 s[6:7], s[20:21], 1
	s_add_u32 s6, s31, s6
	v_fma_f32 v86, -v84, v85, 1.0
	v_fmac_f32_e32 v85, v86, v85
	v_div_scale_f32 v86, vcc, 1.0, v83, 1.0
	v_mul_f32_e32 v87, v86, v85
	v_fma_f32 v88, -v84, v87, v86
	v_fmac_f32_e32 v87, v88, v85
	ds_read_b128 v[88:91], v182
	v_fma_f32 v84, -v84, v87, v86
	v_div_fmas_f32 v84, v84, v85, v87
	v_div_fixup_f32 v86, v84, v83, 1.0
	s_addc_u32 s7, s34, s7
	s_waitcnt lgkmcnt(0)
	v_pk_mul_f32 v[88:89], v[122:123], v[88:89]
	v_pk_mul_f32 v[84:85], v[124:125], v[90:91]
	v_pk_fma_f32 v[78:79], v[78:79], v[86:87], v[88:89] op_sel_hi:[1,0,1] neg_lo:[0,0,1] neg_hi:[0,0,1]
	ds_read_b128 v[88:91], v182 offset:64
	v_pk_fma_f32 v[80:81], v[80:81], v[86:87], v[84:85] op_sel_hi:[1,0,1] neg_lo:[0,0,1] neg_hi:[0,0,1]
	v_mul_f32_e32 v83, v79, v79
	v_fmac_f32_e32 v83, v78, v78
	v_fmac_f32_e32 v83, v80, v80
	s_waitcnt lgkmcnt(0)
	v_pk_mul_f32 v[88:89], v[122:123], v[88:89]
	v_pk_mul_f32 v[84:85], v[124:125], v[90:91]
	v_pk_fma_f32 v[74:75], v[74:75], v[86:87], v[88:89] op_sel_hi:[1,0,1] neg_lo:[0,0,1] neg_hi:[0,0,1]
	ds_read_b128 v[88:91], v182 offset:128
	v_pk_fma_f32 v[76:77], v[76:77], v[86:87], v[84:85] op_sel_hi:[1,0,1] neg_lo:[0,0,1] neg_hi:[0,0,1]
	v_mul_f32_e32 v84, v75, v75
	v_fmac_f32_e32 v84, v74, v74
	v_fmac_f32_e32 v84, v76, v76
	v_fmac_f32_e32 v83, v81, v81
	v_fmac_f32_e32 v84, v77, v77
	s_waitcnt lgkmcnt(0)
	v_pk_mul_f32 v[88:89], v[122:123], v[88:89]
	v_add_f32_e32 v83, v83, v84
	v_pk_mul_f32 v[84:85], v[124:125], v[90:91]
	v_pk_fma_f32 v[70:71], v[70:71], v[86:87], v[88:89] op_sel_hi:[1,0,1] neg_lo:[0,0,1] neg_hi:[0,0,1]
	ds_read_b128 v[88:91], v182 offset:192
	v_pk_fma_f32 v[72:73], v[72:73], v[86:87], v[84:85] op_sel_hi:[1,0,1] neg_lo:[0,0,1] neg_hi:[0,0,1]
	v_mul_f32_e32 v84, v71, v71
	v_fmac_f32_e32 v84, v70, v70
	v_fmac_f32_e32 v84, v72, v72
	v_fmac_f32_e32 v84, v73, v73
	s_waitcnt lgkmcnt(0)
	v_pk_mul_f32 v[88:89], v[122:123], v[88:89]
	v_add_f32_e32 v83, v83, v84
	v_pk_mul_f32 v[84:85], v[124:125], v[90:91]
	v_pk_fma_f32 v[66:67], v[66:67], v[86:87], v[88:89] op_sel_hi:[1,0,1] neg_lo:[0,0,1] neg_hi:[0,0,1]
	ds_read_b128 v[88:91], v182 offset:256
	v_pk_fma_f32 v[68:69], v[68:69], v[86:87], v[84:85] op_sel_hi:[1,0,1] neg_lo:[0,0,1] neg_hi:[0,0,1]
	v_mul_f32_e32 v84, v67, v67
	v_fmac_f32_e32 v84, v66, v66
	v_fmac_f32_e32 v84, v68, v68
	v_fmac_f32_e32 v84, v69, v69
	s_waitcnt lgkmcnt(0)
	v_pk_mul_f32 v[88:89], v[122:123], v[88:89]
	v_add_f32_e32 v83, v83, v84
	v_pk_mul_f32 v[84:85], v[124:125], v[90:91]
	v_pk_fma_f32 v[62:63], v[62:63], v[86:87], v[88:89] op_sel_hi:[1,0,1] neg_lo:[0,0,1] neg_hi:[0,0,1]
	ds_read_b128 v[88:91], v182 offset:320
	v_pk_fma_f32 v[64:65], v[64:65], v[86:87], v[84:85] op_sel_hi:[1,0,1] neg_lo:[0,0,1] neg_hi:[0,0,1]
	v_mul_f32_e32 v84, v63, v63
	v_fmac_f32_e32 v84, v62, v62
	v_fmac_f32_e32 v84, v64, v64
	v_fmac_f32_e32 v84, v65, v65
	s_waitcnt lgkmcnt(0)
	v_pk_mul_f32 v[88:89], v[122:123], v[88:89]
	v_add_f32_e32 v83, v83, v84
	v_pk_mul_f32 v[84:85], v[124:125], v[90:91]
	v_pk_fma_f32 v[58:59], v[58:59], v[86:87], v[88:89] op_sel_hi:[1,0,1] neg_lo:[0,0,1] neg_hi:[0,0,1]
	ds_read_b128 v[88:91], v182 offset:384
	v_pk_fma_f32 v[60:61], v[60:61], v[86:87], v[84:85] op_sel_hi:[1,0,1] neg_lo:[0,0,1] neg_hi:[0,0,1]
	v_mul_f32_e32 v84, v59, v59
	v_fmac_f32_e32 v84, v58, v58
	v_fmac_f32_e32 v84, v60, v60
	v_fmac_f32_e32 v84, v61, v61
	s_waitcnt lgkmcnt(0)
	v_pk_mul_f32 v[88:89], v[122:123], v[88:89]
	v_add_f32_e32 v83, v83, v84
	v_pk_mul_f32 v[84:85], v[124:125], v[90:91]
	v_pk_fma_f32 v[54:55], v[54:55], v[86:87], v[88:89] op_sel_hi:[1,0,1] neg_lo:[0,0,1] neg_hi:[0,0,1]
	ds_read_b128 v[88:91], v182 offset:448
	v_pk_fma_f32 v[56:57], v[56:57], v[86:87], v[84:85] op_sel_hi:[1,0,1] neg_lo:[0,0,1] neg_hi:[0,0,1]
	v_mul_f32_e32 v84, v55, v55
	v_fmac_f32_e32 v84, v54, v54
	v_fmac_f32_e32 v84, v56, v56
	v_fmac_f32_e32 v84, v57, v57
	v_add_f32_e32 v83, v83, v84
	s_waitcnt lgkmcnt(0)
	v_pk_mul_f32 v[84:85], v[124:125], v[90:91]
	v_pk_mul_f32 v[88:89], v[122:123], v[88:89]
	v_pk_fma_f32 v[84:85], v[52:53], v[86:87], v[84:85] op_sel_hi:[1,0,1] neg_lo:[0,0,1] neg_hi:[0,0,1]
	v_pk_fma_f32 v[86:87], v[50:51], v[86:87], v[88:89] op_sel_hi:[1,0,1] neg_lo:[0,0,1] neg_hi:[0,0,1]
	s_nop 0
	v_mul_f32_e32 v50, v87, v87
	v_fmac_f32_e32 v50, v86, v86
	v_fmac_f32_e32 v50, v84, v84
	v_fmac_f32_e32 v50, v85, v85
	v_add_f32_e32 v50, v83, v50
	v_mov_b32_e32 v51, v50
	s_nop 1
	v_permlane16_swap_b32_e32 v50, v51
	v_add_f32_e32 v50, v50, v51
	v_mov_b32_e32 v51, v50
	s_nop 1
	v_permlane32_swap_b32_e32 v50, v51
	v_add_f32_e32 v50, v50, v51
	v_fmamk_f32 v50, v50, 0x3c000000, v146
	v_cmp_gt_f32_e32 vcc, s33, v50
	v_mul_f32_e32 v51, 0x4b800000, v50
	v_ashrrev_i32_e32 v83, 31, v82
	v_cndmask_b32_e32 v50, v50, v51, vcc
	v_rsq_f32_e32 v50, v50
	s_nop 0
	v_mul_f32_e32 v51, 0x45800000, v50
	v_cndmask_b32_e32 v50, v50, v51, vcc
	v_mul_f32_e32 v95, 0x3f24fd5c, v50
	v_lshlrev_b64 v[50:51], 11, v[82:83]
	v_lshl_add_u64 v[90:91], s[6:7], 0, v[50:51]
	v_mov_b32_e32 v50, v119
	v_mul_f32_e32 v78, v78, v95
	v_lshlrev_b32_e32 v92, 2, v50
	v_ashrrev_i32_e32 v93, 31, v92
	v_lshl_add_u64 v[88:89], v[92:93], 2, s[10:11]
	global_load_dwordx4 v[188:191], v[88:89], off
	global_load_dwordx4 v[192:195], v[88:89], off offset:64
	global_load_dwordx4 v[196:199], v[88:89], off offset:128
	global_load_dwordx4 v[200:203], v[88:89], off offset:192
	global_load_dwordx4 v[204:207], v[88:89], off offset:256
	global_load_dwordx4 v[208:211], v[88:89], off offset:320
	global_load_dwordx4 v[212:215], v[88:89], off offset:384
	global_load_dwordx4 v[216:219], v[88:89], off offset:448
	s_waitcnt vmcnt(0)
; __device__ __forceinline__ void phase_attn(KP P, char* smem, const int wv) {
;     ...
;         for (int et = 0; et < 8; ++et) {
;           f32x4 o1 = *(const f32x4*)(sO + (rg * 32 + qt * 16 + fr) * A_LDO + et * 16 + fq * 4);
;           f32x4 o = oacc[qt][et] * rl - o1 * lam;
;           oacc[qt][et] = o;
;           ss += o[0] * o[0] + o[1] * o[1] + o[2] * o[2] + o[3] * o[3];
;         }
;         ss = xsum_16_32(ss);
;         float rstd = rsqrtf(ss * (1.f / 128.f) + EPS) * (1.f - LAMBDA_INIT);
;         bfu* dst = ao + (size_t)(qrow0 + rg * 32 + qt * 16 + fr) * 1024 + h * 128;
;         int fqe = fq;
;         asm volatile("" : "+v"(fqe));
; #pragma unroll
;         for (int et = 0; et < 8; ++et) {
;           int e0 = et * 16 + fqe * 4;
;           f32x4 sw = *(const f32x4*)(subln + e0);
;           uint2 pk;
;           pk.x = cvt_pk_bf16(oacc[qt][et][0] * rstd * sw[0], oacc[qt][et][1] * rstd * sw[1]);
;           pk.y = cvt_pk_bf16(oacc[qt][et][2] * rstd * sw[2], oacc[qt][et][3] * rstd * sw[3]);
;           *(uint2*)(dst + e0) = pk;
;         }
	v_mul_f32_e32 v50, v188, v78
	v_mul_f32_e32 v78, v79, v95
	v_mul_f32_e32 v51, v189, v78
	v_cvt_pk_bf16_f32 v78, v50, v51
	v_mul_f32_e32 v50, v80, v95
	v_mul_f32_e32 v51, v81, v95
	v_mul_f32_e32 v50, v190, v50
	v_mul_f32_e32 v51, v191, v51
	v_cvt_pk_bf16_f32 v79, v50, v51
	v_lshl_add_u64 v[50:51], v[92:93], 1, v[90:91]
	global_store_dwordx2 v[50:51], v[78:79], off
	v_mul_f32_e32 v52, v74, v95
	v_mul_f32_e32 v53, v75, v95
	v_mul_f32_e32 v74, v77, v95
	v_mul_f32_e32 v52, v192, v52
	v_mul_f32_e32 v53, v193, v53
	v_cvt_pk_bf16_f32 v52, v52, v53
	v_mul_f32_e32 v53, v76, v95
	v_mul_f32_e32 v53, v194, v53
	v_mul_f32_e32 v74, v195, v74
	v_cvt_pk_bf16_f32 v53, v53, v74
	global_store_dwordx2 v[50:51], v[52:53], off offset:32
	v_mul_f32_e32 v52, v70, v95
	v_mul_f32_e32 v53, v71, v95
	v_mul_f32_e32 v70, v73, v95
	v_mul_f32_e32 v52, v52, v196
	v_mul_f32_e32 v53, v53, v197
	v_cvt_pk_bf16_f32 v52, v52, v53
	v_mul_f32_e32 v53, v72, v95
	v_mul_f32_e32 v53, v53, v198
	v_mul_f32_e32 v70, v70, v199
	v_cvt_pk_bf16_f32 v53, v53, v70
	global_store_dwordx2 v[50:51], v[52:53], off offset:64
	v_mul_f32_e32 v52, v66, v95
	v_mul_f32_e32 v53, v67, v95
	v_mul_f32_e32 v66, v69, v95
	v_mul_f32_e32 v52, v52, v200
	v_mul_f32_e32 v53, v53, v201
	v_cvt_pk_bf16_f32 v52, v52, v53
	v_mul_f32_e32 v53, v68, v95
	v_mul_f32_e32 v53, v53, v202
	v_mul_f32_e32 v66, v66, v203
	v_cvt_pk_bf16_f32 v53, v53, v66
	global_store_dwordx2 v[50:51], v[52:53], off offset:96
	v_mul_f32_e32 v52, v62, v95
	v_mul_f32_e32 v53, v63, v95
	v_mul_f32_e32 v62, v65, v95
	v_mul_f32_e32 v52, v52, v204
	v_mul_f32_e32 v53, v53, v205
	v_cvt_pk_bf16_f32 v52, v52, v53
	v_mul_f32_e32 v53, v64, v95
	v_mul_f32_e32 v53, v53, v206
	v_mul_f32_e32 v62, v62, v207
	v_cvt_pk_bf16_f32 v53, v53, v62
	global_store_dwordx2 v[50:51], v[52:53], off offset:128
	v_mul_f32_e32 v52, v58, v95
	v_mul_f32_e32 v53, v59, v95
	v_mul_f32_e32 v58, v61, v95
	v_mul_f32_e32 v52, v52, v208
	v_mul_f32_e32 v53, v53, v209
	v_cvt_pk_bf16_f32 v52, v52, v53
	v_mul_f32_e32 v53, v60, v95
	v_mul_f32_e32 v53, v53, v210
	v_mul_f32_e32 v58, v58, v211
	v_cvt_pk_bf16_f32 v53, v53, v58
	global_store_dwordx2 v[50:51], v[52:53], off offset:160
	v_mul_f32_e32 v52, v54, v95
	v_mul_f32_e32 v53, v55, v95
	v_mul_f32_e32 v54, v57, v95
	v_mul_f32_e32 v52, v52, v212
	v_mul_f32_e32 v53, v53, v213
	v_cvt_pk_bf16_f32 v52, v52, v53
	v_mul_f32_e32 v53, v56, v95
	v_mul_f32_e32 v53, v53, v214
	v_mul_f32_e32 v54, v54, v215
	v_cvt_pk_bf16_f32 v53, v53, v54
	global_store_dwordx2 v[50:51], v[52:53], off offset:192
	v_mul_f32_e32 v56, v86, v95
	v_mul_f32_e32 v52, v56, v216
	v_mul_f32_e32 v56, v87, v95
	v_mul_f32_e32 v53, v56, v217
	v_cvt_pk_bf16_f32 v52, v52, v53
	v_mul_f32_e32 v53, v84, v95
	v_mul_f32_e32 v53, v53, v218
	v_mul_f32_e32 v54, v85, v95
	v_mul_f32_e32 v54, v54, v219
	v_cvt_pk_bf16_f32 v53, v53, v54
	global_store_dwordx2 v[50:51], v[52:53], off offset:224
	v_div_scale_f32 v50, s[8:9], v94, v94, 1.0
	v_rcp_f32_e32 v51, v50
	s_nop 0
	v_fma_f32 v52, -v50, v51, 1.0
	v_fmac_f32_e32 v51, v52, v51
	v_div_scale_f32 v52, vcc, 1.0, v94, 1.0
	v_mul_f32_e32 v53, v52, v51
	v_fma_f32 v54, -v50, v53, v52
	v_fmac_f32_e32 v53, v54, v51
	v_fma_f32 v50, -v50, v53, v52
	v_div_fmas_f32 v50, v50, v51, v53
	v_div_fixup_f32 v56, v50, v94, 1.0
	ds_read_b128 v[50:53], v182 offset:8448
	s_waitcnt lgkmcnt(0)
	v_pk_mul_f32 v[52:53], v[124:125], v[52:53]
	v_pk_mul_f32 v[50:51], v[122:123], v[50:51]
	v_pk_fma_f32 v[48:49], v[48:49], v[56:57], v[52:53] op_sel_hi:[1,0,1] neg_lo:[0,0,1] neg_hi:[0,0,1]
	ds_read_b128 v[52:55], v182 offset:8512
	v_pk_fma_f32 v[50:51], v[46:47], v[56:57], v[50:51] op_sel_hi:[1,0,1] neg_lo:[0,0,1] neg_hi:[0,0,1]
	s_waitcnt lgkmcnt(0)
	v_pk_mul_f32 v[52:53], v[122:123], v[52:53]
	v_mul_f32_e32 v57, v51, v51
	v_fmac_f32_e32 v57, v50, v50
	v_fmac_f32_e32 v57, v48, v48
	v_fmac_f32_e32 v57, v49, v49
	v_pk_mul_f32 v[46:47], v[124:125], v[54:55]
	v_pk_fma_f32 v[42:43], v[42:43], v[56:57], v[52:53] op_sel_hi:[1,0,1] neg_lo:[0,0,1] neg_hi:[0,0,1]
	ds_read_b128 v[52:55], v182 offset:8576
	v_pk_fma_f32 v[44:45], v[44:45], v[56:57], v[46:47] op_sel_hi:[1,0,1] neg_lo:[0,0,1] neg_hi:[0,0,1]
	v_mul_f32_e32 v46, v43, v43
	v_fmac_f32_e32 v46, v42, v42
	v_fmac_f32_e32 v46, v44, v44
	v_fmac_f32_e32 v46, v45, v45
	v_add_f32_e32 v57, v57, v46
	s_waitcnt lgkmcnt(0)
	v_pk_mul_f32 v[52:53], v[122:123], v[52:53]
	v_pk_mul_f32 v[46:47], v[124:125], v[54:55]
	v_pk_fma_f32 v[38:39], v[38:39], v[56:57], v[52:53] op_sel_hi:[1,0,1] neg_lo:[0,0,1] neg_hi:[0,0,1]
	ds_read_b128 v[52:55], v182 offset:8640
	v_pk_fma_f32 v[40:41], v[40:41], v[56:57], v[46:47] op_sel_hi:[1,0,1] neg_lo:[0,0,1] neg_hi:[0,0,1]
	v_mul_f32_e32 v46, v39, v39
	v_fmac_f32_e32 v46, v38, v38
	v_fmac_f32_e32 v46, v40, v40
	v_fmac_f32_e32 v46, v41, v41
	v_add_f32_e32 v57, v57, v46
	s_waitcnt lgkmcnt(0)
	v_pk_mul_f32 v[52:53], v[122:123], v[52:53]
	v_pk_mul_f32 v[46:47], v[124:125], v[54:55]
	v_pk_fma_f32 v[34:35], v[34:35], v[56:57], v[52:53] op_sel_hi:[1,0,1] neg_lo:[0,0,1] neg_hi:[0,0,1]
	ds_read_b128 v[52:55], v182 offset:8704
	v_pk_fma_f32 v[36:37], v[36:37], v[56:57], v[46:47] op_sel_hi:[1,0,1] neg_lo:[0,0,1] neg_hi:[0,0,1]
	v_mul_f32_e32 v46, v35, v35
	v_fmac_f32_e32 v46, v34, v34
	v_fmac_f32_e32 v46, v36, v36
	v_fmac_f32_e32 v46, v37, v37
	v_add_f32_e32 v57, v57, v46
	s_waitcnt lgkmcnt(0)
; __device__ __forceinline__ void phase_attn(KP P, char* smem, const int wv) {
;     ...
;         for (int et = 0; et < 8; ++et) {
;           f32x4 o1 = *(const f32x4*)(sO + (rg * 32 + qt * 16 + fr) * A_LDO + et * 16 + fq * 4);
;           f32x4 o = oacc[qt][et] * rl - o1 * lam;
;           oacc[qt][et] = o;
;           ss += o[0] * o[0] + o[1] * o[1] + o[2] * o[2] + o[3] * o[3];
;         }
;         ss = xsum_16_32(ss);
;         float rstd = rsqrtf(ss * (1.f / 128.f) + EPS) * (1.f - LAMBDA_INIT);
;         bfu* dst = ao + (size_t)(qrow0 + rg * 32 + qt * 16 + fr) * 1024 + h * 128;
;         int fqe = fq;
;         asm volatile("" : "+v"(fqe));
; #pragma unroll
;         for (int et = 0; et < 8; ++et) {
;           int e0 = et * 16 + fqe * 4;
;           f32x4 sw = *(const f32x4*)(subln + e0);
;           uint2 pk;
;           pk.x = cvt_pk_bf16(oacc[qt][et][0] * rstd * sw[0], oacc[qt][et][1] * rstd * sw[1]);
;           pk.y = cvt_pk_bf16(oacc[qt][et][2] * rstd * sw[2], oacc[qt][et][3] * rstd * sw[3]);
;           *(uint2*)(dst + e0) = pk;
;         }
	v_pk_mul_f32 v[52:53], v[122:123], v[52:53]
	v_pk_mul_f32 v[46:47], v[124:125], v[54:55]
	v_pk_fma_f32 v[30:31], v[30:31], v[56:57], v[52:53] op_sel_hi:[1,0,1] neg_lo:[0,0,1] neg_hi:[0,0,1]
	ds_read_b128 v[52:55], v182 offset:8768
	v_pk_fma_f32 v[32:33], v[32:33], v[56:57], v[46:47] op_sel_hi:[1,0,1] neg_lo:[0,0,1] neg_hi:[0,0,1]
	v_mul_f32_e32 v46, v31, v31
	v_fmac_f32_e32 v46, v30, v30
	v_fmac_f32_e32 v46, v32, v32
	v_fmac_f32_e32 v46, v33, v33
	v_add_f32_e32 v57, v57, v46
	s_waitcnt lgkmcnt(0)
	v_pk_mul_f32 v[52:53], v[122:123], v[52:53]
	v_pk_mul_f32 v[46:47], v[124:125], v[54:55]
	v_pk_fma_f32 v[26:27], v[26:27], v[56:57], v[52:53] op_sel_hi:[1,0,1] neg_lo:[0,0,1] neg_hi:[0,0,1]
	ds_read_b128 v[52:55], v182 offset:8832
	v_pk_fma_f32 v[28:29], v[28:29], v[56:57], v[46:47] op_sel_hi:[1,0,1] neg_lo:[0,0,1] neg_hi:[0,0,1]
	v_mul_f32_e32 v46, v27, v27
	v_fmac_f32_e32 v46, v26, v26
	v_fmac_f32_e32 v46, v28, v28
	v_fmac_f32_e32 v46, v29, v29
	v_add_f32_e32 v57, v57, v46
	s_waitcnt lgkmcnt(0)
	v_pk_mul_f32 v[52:53], v[122:123], v[52:53]
	v_pk_mul_f32 v[46:47], v[124:125], v[54:55]
	v_pk_fma_f32 v[22:23], v[22:23], v[56:57], v[52:53] op_sel_hi:[1,0,1] neg_lo:[0,0,1] neg_hi:[0,0,1]
	ds_read_b128 v[52:55], v182 offset:8896
	v_pk_fma_f32 v[24:25], v[24:25], v[56:57], v[46:47] op_sel_hi:[1,0,1] neg_lo:[0,0,1] neg_hi:[0,0,1]
	v_mul_f32_e32 v46, v23, v23
	v_fmac_f32_e32 v46, v22, v22
	v_fmac_f32_e32 v46, v24, v24
	v_fmac_f32_e32 v46, v25, v25
	v_add_f32_e32 v57, v57, v46
	s_waitcnt lgkmcnt(0)
	v_pk_mul_f32 v[52:53], v[122:123], v[52:53]
	v_pk_mul_f32 v[46:47], v[124:125], v[54:55]
	v_pk_fma_f32 v[18:19], v[18:19], v[56:57], v[52:53] op_sel_hi:[1,0,1] neg_lo:[0,0,1] neg_hi:[0,0,1]
	v_mov_b32_e32 v52, v119
	v_pk_fma_f32 v[20:21], v[20:21], v[56:57], v[46:47] op_sel_hi:[1,0,1] neg_lo:[0,0,1] neg_hi:[0,0,1]
	v_lshlrev_b32_e32 v54, 2, v52
	v_ashrrev_i32_e32 v55, 31, v54
	v_lshl_add_u64 v[52:53], v[54:55], 2, s[10:11]
	v_mul_f32_e32 v46, v19, v19
	v_fmac_f32_e32 v46, v18, v18
	v_fmac_f32_e32 v46, v20, v20
	v_fmac_f32_e32 v46, v21, v21
	v_add_f32_e32 v46, v57, v46
	v_mov_b32_e32 v47, v46
	s_nop 1
	v_permlane16_swap_b32_e32 v46, v47
	v_add_f32_e32 v46, v46, v47
	v_mov_b32_e32 v47, v46
	s_nop 1
	v_permlane32_swap_b32_e32 v46, v47
	v_add_f32_e32 v46, v46, v47
	v_fmamk_f32 v46, v46, 0x3c000000, v146
	v_cmp_gt_f32_e32 vcc, s33, v46
	v_mul_f32_e32 v47, 0x4b800000, v46
	s_nop 0
	v_cndmask_b32_e32 v46, v46, v47, vcc
	v_rsq_f32_e32 v46, v46
	s_nop 0
	v_mul_f32_e32 v47, 0x45800000, v46
	v_cndmask_b32_e32 v46, v46, v47, vcc
	v_mul_f32_e32 v56, 0x3f24fd5c, v46
	v_add_u32_e32 v46, 16, v82
	v_ashrrev_i32_e32 v47, 31, v46
	v_lshlrev_b64 v[46:47], 11, v[46:47]
	v_lshl_add_u64 v[46:47], s[6:7], 0, v[46:47]
	v_mul_f32_e32 v50, v50, v56
	v_mul_f32_e32 v51, v51, v56
	v_mul_f32_e32 v48, v48, v56
	v_mul_f32_e32 v49, v49, v56
	v_lshl_add_u64 v[46:47], v[54:55], 1, v[46:47]
	v_mul_f32_e32 v42, v42, v56
	v_mul_f32_e32 v43, v43, v56
	v_mul_f32_e32 v38, v38, v56
	v_mul_f32_e32 v39, v39, v56
	v_mul_f32_e32 v34, v34, v56
	v_mul_f32_e32 v35, v35, v56
	v_mul_f32_e32 v30, v30, v56
	v_mul_f32_e32 v31, v31, v56
	v_mul_f32_e32 v26, v26, v56
	v_mul_f32_e32 v27, v27, v56
	v_mul_f32_e32 v22, v22, v56
	v_mul_f32_e32 v23, v23, v56
	v_mul_f32_e32 v18, v18, v56
	v_mul_f32_e32 v19, v19, v56
	v_mul_f32_e32 v50, v188, v50
	v_mul_f32_e32 v51, v189, v51
	v_cvt_pk_bf16_f32 v50, v50, v51
	v_mul_f32_e32 v48, v190, v48
	v_mul_f32_e32 v49, v191, v49
	v_cvt_pk_bf16_f32 v51, v48, v49
	global_store_dwordx2 v[46:47], v[50:51], off
	v_mul_f32_e32 v42, v192, v42
	v_mul_f32_e32 v43, v193, v43
	v_cvt_pk_bf16_f32 v42, v42, v43
	v_mul_f32_e32 v43, v44, v56
	v_mul_f32_e32 v43, v194, v43
	v_mul_f32_e32 v44, v45, v56
	v_mul_f32_e32 v44, v195, v44
	v_cvt_pk_bf16_f32 v43, v43, v44
	global_store_dwordx2 v[46:47], v[42:43], off offset:32
	v_mul_f32_e32 v38, v38, v196
	v_mul_f32_e32 v39, v39, v197
	v_cvt_pk_bf16_f32 v38, v38, v39
	v_mul_f32_e32 v39, v40, v56
	v_mul_f32_e32 v39, v39, v198
	v_mul_f32_e32 v40, v41, v56
	v_mul_f32_e32 v40, v40, v199
	v_cvt_pk_bf16_f32 v39, v39, v40
	global_store_dwordx2 v[46:47], v[38:39], off offset:64
	v_mul_f32_e32 v34, v34, v200
	v_mul_f32_e32 v35, v35, v201
	v_cvt_pk_bf16_f32 v34, v34, v35
	v_mul_f32_e32 v35, v36, v56
	v_mul_f32_e32 v35, v35, v202
	v_mul_f32_e32 v36, v37, v56
	v_mul_f32_e32 v36, v36, v203
	v_cvt_pk_bf16_f32 v35, v35, v36
	global_store_dwordx2 v[46:47], v[34:35], off offset:96
	v_mul_f32_e32 v30, v30, v204
	v_mul_f32_e32 v31, v31, v205
	v_cvt_pk_bf16_f32 v30, v30, v31
	v_mul_f32_e32 v31, v32, v56
	v_mul_f32_e32 v31, v31, v206
	v_mul_f32_e32 v32, v33, v56
	v_mul_f32_e32 v32, v32, v207
	v_cvt_pk_bf16_f32 v31, v31, v32
	global_store_dwordx2 v[46:47], v[30:31], off offset:128
	v_mul_f32_e32 v26, v26, v208
	v_mul_f32_e32 v27, v27, v209
	v_cvt_pk_bf16_f32 v26, v26, v27
	v_mul_f32_e32 v27, v28, v56
	v_mul_f32_e32 v27, v27, v210
	v_mul_f32_e32 v28, v29, v56
	v_mul_f32_e32 v28, v28, v211
	v_cvt_pk_bf16_f32 v27, v27, v28
	global_store_dwordx2 v[46:47], v[26:27], off offset:160
	v_mul_f32_e32 v22, v22, v212
	v_mul_f32_e32 v23, v23, v213
	v_cvt_pk_bf16_f32 v22, v22, v23
	v_mul_f32_e32 v23, v24, v56
	v_mul_f32_e32 v23, v23, v214
	v_mul_f32_e32 v24, v25, v56
	v_mul_f32_e32 v24, v24, v215
	v_cvt_pk_bf16_f32 v23, v23, v24
	global_store_dwordx2 v[46:47], v[22:23], off offset:192
	v_mul_f32_e32 v18, v18, v216
	v_mul_f32_e32 v19, v19, v217
	v_cvt_pk_bf16_f32 v18, v18, v19
	v_mul_f32_e32 v19, v20, v56
	v_mul_f32_e32 v19, v19, v218
	v_mul_f32_e32 v20, v21, v56
	v_mul_f32_e32 v20, v20, v219
	v_cvt_pk_bf16_f32 v19, v19, v20
	global_store_dwordx2 v[46:47], v[18:19], off offset:224
	s_branch .LBB0_30

; #define PG8_STAGE(bufoff, gbase) do { _Pragma("unroll") for (int _i = 0; _i < 2; ++_i) \
;     __builtin_amdgcn_global_load_lds((const unsigned*)((const char*)(gbase) + voff[_i]), (LAS unsigned*)(lds + (bufoff) + ldsw + _i * 8192), 16, 0, 0); } while (0)
; #define PG8_LDA(dst, b, h) do { _Pragma("unroll") for (int m = 0; m < 4; ++m) _Pragma("unroll") for (int k = 0; k < 2; ++k) dst[m][k] = *(const LAS bf16x8*)(lds + PG8_SA(b, h) + aoff + m * 2048 + k * 1024); } while (0)
; #define PG8_LDB(dst, b, h) do { _Pragma("unroll") for (int n = 0; n < 2; ++n) _Pragma("unroll") for (int k = 0; k < 2; ++k) dst[n][k] = *(const LAS bf16x8*)(lds + PG8_SB(b, h) + boff + n * 2048 + k * 1024); } while (0)
; #define PG8_MMA(ai, bj, At, Bt_) do { __builtin_amdgcn_s_setprio(1); _Pragma("unroll") for (int m = 0; m < 4; ++m) _Pragma("unroll") for (int n = 0; n < 2; ++n) _Pragma("unroll") for (int k = 0; k < 2; ++k) \
;     acc[ai][bj][m][n] = __builtin_amdgcn_mfma_f32_16x16x32_bf16(Bt_[n][k], At[m][k], acc[ai][bj][m][n], 0, 0, 0); __builtin_amdgcn_s_setprio(0); } while (0)
; #define PG8_WAIT_V(n) asm volatile("s_waitcnt vmcnt(" #n ")" ::: "memory")
; #define PG8_WAIT_L(n) asm volatile("s_waitcnt lgkmcnt(" #n ")" ::: "memory")
; #define PG8_BAR __builtin_amdgcn_s_barrier()
; #define PG8_SCHED __builtin_amdgcn_sched_barrier(0)
; template <int EPI>
; __device__ __forceinline__ void gemm_phase(KP P, const bfu* __restrict__ A, const bfu* __restrict__ Bt, int K, int ntn, char* smem, const int wv) {
;     ...
;     for (int t = 0; t < nt; t += 2) {
;       const bool last = (t == nt - 2);
;       const char* a1 = cA + (size_t)(t + 1) * kstep;
;       const char* a2 = last ? nA : cA + (size_t)(t + 2) * kstep;
;       const char* b2 = last ? nB : cB + (size_t)(t + 2) * kstep;
;       const char* a3 = a2 + kstep;
;       const char* b3 = b2 + kstep;
;       PG8_LDB(B0, 0, 0); PG8_SCHED; PG8_LDA(At, 0, 0); PG8_STAGE(PG8_SA(1, 1), a1 + hstep);
;       PG8_WAIT_L(8); PG8_BAR; PG8_WAIT_L(0); PG8_MMA(0, 0, At, B0); PG8_BAR; PG8_SCHED;
;       PG8_LDB(B1, 0, 1); PG8_STAGE(PG8_SB(0, 0), b2);
;       PG8_BAR; PG8_WAIT_L(0); PG8_MMA(0, 1, At, B1); PG8_BAR;
;       PG8_LDA(At, 0, 1); PG8_STAGE(PG8_SA(0, 0), a2);
;       PG8_BAR; PG8_WAIT_L(0); PG8_MMA(1, 0, At, B0); PG8_BAR; PG8_SCHED;
;       PG8_STAGE(PG8_SB(0, 1), b2 + hstep);
;       PG8_WAIT_V(6); PG8_BAR; PG8_MMA(1, 1, At, B1); PG8_BAR;
.LBB0_310:
	v_add_u32_e32 v0, s23, v145
	s_add_u32 s26, s76, s24
	ds_read_b128 v[150:153], v0
	ds_read_b128 v[154:157], v0 offset:1024
	ds_read_b128 v[158:161], v0 offset:2048
	ds_read_b128 v[180:183], v0 offset:3072
	s_addc_u32 s27, s77, s25
	s_add_u32 s26, s26, 0x11290100
	s_addc_u32 s27, s27, 0
	s_add_u32 s81, s78, s24
	s_addc_u32 s82, s79, s25
	s_cmpk_eq_i32 s24, 0xf00
	s_cselect_b32 s31, s21, s27
	s_cselect_b32 s30, s5, s26
	s_cselect_b32 s27, s75, s82
	s_cselect_b32 s26, s11, s81
	v_lshl_add_u64 v[162:163], v[138:139], 0, s[24:25]
	s_add_i32 m0, s41, 0xc000
	ds_read_b128 v[184:187], v149
	ds_read_b128 v[188:191], v149 offset:1024
	ds_read_b128 v[192:195], v149 offset:2048
	ds_read_b128 v[196:199], v149 offset:3072
	ds_read_b128 v[200:203], v149 offset:4096
	ds_read_b128 v[204:207], v149 offset:5120
	ds_read_b128 v[208:211], v149 offset:6144
	ds_read_b128 v[212:215], v149 offset:7168
	global_load_lds_dwordx4 v[162:163], off
	v_lshl_add_u64 v[162:163], v[140:141], 0, s[24:25]
	s_add_i32 m0, s41, 0xe000
	s_nop 0
	global_load_lds_dwordx4 v[162:163], off
	s_waitcnt lgkmcnt(8)
	s_barrier
	s_waitcnt lgkmcnt(0)
	s_setprio 1
	s_waitcnt lgkmcnt(0)
	v_mfma_f32_16x16x32_bf16 v[2:5], v[150:153], v[184:187], v[2:5]
	v_mfma_f32_16x16x32_bf16 v[6:9], v[158:161], v[184:187], v[6:9]
	v_mfma_f32_16x16x32_bf16 v[18:21], v[150:153], v[192:195], v[18:21]
	v_mfma_f32_16x16x32_bf16 v[22:25], v[158:161], v[192:195], v[22:25]
	v_mfma_f32_16x16x32_bf16 v[34:37], v[150:153], v[200:203], v[34:37]
	v_mfma_f32_16x16x32_bf16 v[38:41], v[158:161], v[200:203], v[38:41]
	v_mfma_f32_16x16x32_bf16 v[50:53], v[150:153], v[208:211], v[50:53]
	v_mfma_f32_16x16x32_bf16 v[54:57], v[158:161], v[208:211], v[54:57]
	v_mfma_f32_16x16x32_bf16 v[2:5], v[154:157], v[188:191], v[2:5]
	v_mfma_f32_16x16x32_bf16 v[6:9], v[180:183], v[188:191], v[6:9]
	v_mfma_f32_16x16x32_bf16 v[18:21], v[154:157], v[196:199], v[18:21]
	v_mfma_f32_16x16x32_bf16 v[22:25], v[180:183], v[196:199], v[22:25]
	v_mfma_f32_16x16x32_bf16 v[34:37], v[154:157], v[204:207], v[34:37]
	v_mfma_f32_16x16x32_bf16 v[38:41], v[180:183], v[204:207], v[38:41]
	v_mfma_f32_16x16x32_bf16 v[50:53], v[154:157], v[212:215], v[50:53]
	v_mfma_f32_16x16x32_bf16 v[54:57], v[180:183], v[212:215], v[54:57]
	s_setprio 0
	s_barrier
	s_mov_b32 m0, s39
	v_add_u32_e32 v0, s43, v145
	v_lshl_add_u64 v[162:163], s[26:27], 0, v[130:131]
	ds_read_b128 v[216:219], v0
	ds_read_b128 v[220:223], v0 offset:1024
	ds_read_b128 v[224:227], v0 offset:2048
	ds_read_b128 v[228:231], v0 offset:3072
	global_load_lds_dwordx4 v[162:163], off
	v_lshl_add_u64 v[232:233], s[26:27], 0, v[132:133]
	s_mov_b32 m0, s40
	s_nop 0
	global_load_lds_dwordx4 v[232:233], off
	s_barrier
	s_waitcnt lgkmcnt(0)
	s_setprio 1
	s_waitcnt lgkmcnt(0)
	v_mfma_f32_16x16x32_bf16 v[10:13], v[216:219], v[184:187], v[10:13]
	v_mfma_f32_16x16x32_bf16 v[14:17], v[224:227], v[184:187], v[14:17]
	v_mfma_f32_16x16x32_bf16 v[26:29], v[216:219], v[192:195], v[26:29]
	v_mfma_f32_16x16x32_bf16 v[30:33], v[224:227], v[192:195], v[30:33]
	v_mfma_f32_16x16x32_bf16 v[42:45], v[216:219], v[200:203], v[42:45]
	v_mfma_f32_16x16x32_bf16 v[46:49], v[224:227], v[200:203], v[46:49]
	v_mfma_f32_16x16x32_bf16 v[58:61], v[216:219], v[208:211], v[58:61]
	v_mfma_f32_16x16x32_bf16 v[62:65], v[224:227], v[208:211], v[62:65]
	v_mfma_f32_16x16x32_bf16 v[10:13], v[220:223], v[188:191], v[10:13]
	v_mfma_f32_16x16x32_bf16 v[14:17], v[228:231], v[188:191], v[14:17]
	v_mfma_f32_16x16x32_bf16 v[26:29], v[220:223], v[196:199], v[26:29]
	v_mfma_f32_16x16x32_bf16 v[30:33], v[228:231], v[196:199], v[30:33]
	v_mfma_f32_16x16x32_bf16 v[42:45], v[220:223], v[204:207], v[42:45]
	v_mfma_f32_16x16x32_bf16 v[46:49], v[228:231], v[204:207], v[46:49]
	v_mfma_f32_16x16x32_bf16 v[58:61], v[220:223], v[212:215], v[58:61]
	v_mfma_f32_16x16x32_bf16 v[62:65], v[228:231], v[212:215], v[62:65]
	s_setprio 0
	s_mov_b32 m0, s41
	v_lshl_add_u64 v[234:235], s[30:31], 0, v[130:131]
	s_barrier
	ds_read_b128 v[184:187], v149 offset:16384
	ds_read_b128 v[188:191], v149 offset:17408
	ds_read_b128 v[192:195], v149 offset:18432
	ds_read_b128 v[196:199], v149 offset:19456
	ds_read_b128 v[200:203], v149 offset:20480
	ds_read_b128 v[204:207], v149 offset:21504
	ds_read_b128 v[208:211], v149 offset:22528
	ds_read_b128 v[212:215], v149 offset:23552
	global_load_lds_dwordx4 v[234:235], off
	v_lshl_add_u64 v[236:237], s[30:31], 0, v[132:133]
	s_mov_b32 m0, s42
	s_nop 0
	global_load_lds_dwordx4 v[236:237], off
	s_barrier
	s_waitcnt lgkmcnt(0)
	s_setprio 1
	s_waitcnt lgkmcnt(0)
	v_mfma_f32_16x16x32_bf16 v[66:69], v[150:153], v[184:187], v[66:69]
	v_mfma_f32_16x16x32_bf16 v[70:73], v[158:161], v[184:187], v[70:73]
	v_mfma_f32_16x16x32_bf16 v[82:85], v[150:153], v[192:195], v[82:85]
	v_mfma_f32_16x16x32_bf16 v[86:89], v[158:161], v[192:195], v[86:89]
	v_mfma_f32_16x16x32_bf16 v[98:101], v[150:153], v[200:203], v[98:101]
	v_mfma_f32_16x16x32_bf16 v[102:105], v[158:161], v[200:203], v[102:105]
	v_mfma_f32_16x16x32_bf16 v[114:117], v[150:153], v[208:211], v[114:117]
	v_mfma_f32_16x16x32_bf16 v[118:121], v[158:161], v[208:211], v[118:121]
	v_mfma_f32_16x16x32_bf16 v[66:69], v[154:157], v[188:191], v[66:69]
	v_mfma_f32_16x16x32_bf16 v[70:73], v[180:183], v[188:191], v[70:73]
	v_mfma_f32_16x16x32_bf16 v[82:85], v[154:157], v[196:199], v[82:85]
	v_mfma_f32_16x16x32_bf16 v[86:89], v[180:183], v[196:199], v[86:89]
	v_mfma_f32_16x16x32_bf16 v[98:101], v[154:157], v[204:207], v[98:101]
	v_mfma_f32_16x16x32_bf16 v[102:105], v[180:183], v[204:207], v[102:105]
	v_mfma_f32_16x16x32_bf16 v[114:117], v[154:157], v[212:215], v[114:117]
	v_mfma_f32_16x16x32_bf16 v[118:121], v[180:183], v[212:215], v[118:121]
	s_setprio 0
	s_barrier
; #define PG8_STAGE(bufoff, gbase) do { _Pragma("unroll") for (int _i = 0; _i < 2; ++_i) \
;     __builtin_amdgcn_global_load_lds((const unsigned*)((const char*)(gbase) + voff[_i]), (LAS unsigned*)(lds + (bufoff) + ldsw + _i * 8192), 16, 0, 0); } while (0)
; #define PG8_LDA(dst, b, h) do { _Pragma("unroll") for (int m = 0; m < 4; ++m) _Pragma("unroll") for (int k = 0; k < 2; ++k) dst[m][k] = *(const LAS bf16x8*)(lds + PG8_SA(b, h) + aoff + m * 2048 + k * 1024); } while (0)
; #define PG8_LDB(dst, b, h) do { _Pragma("unroll") for (int n = 0; n < 2; ++n) _Pragma("unroll") for (int k = 0; k < 2; ++k) dst[n][k] = *(const LAS bf16x8*)(lds + PG8_SB(b, h) + boff + n * 2048 + k * 1024); } while (0)
; #define PG8_MMA(ai, bj, At, Bt_) do { __builtin_amdgcn_s_setprio(1); _Pragma("unroll") for (int m = 0; m < 4; ++m) _Pragma("unroll") for (int n = 0; n < 2; ++n) _Pragma("unroll") for (int k = 0; k < 2; ++k) \
;     acc[ai][bj][m][n] = __builtin_amdgcn_mfma_f32_16x16x32_bf16(Bt_[n][k], At[m][k], acc[ai][bj][m][n], 0, 0, 0); __builtin_amdgcn_s_setprio(0); } while (0)
; #define PG8_WAIT_V(n) asm volatile("s_waitcnt vmcnt(" #n ")" ::: "memory")
; #define PG8_WAIT_L(n) asm volatile("s_waitcnt lgkmcnt(" #n ")" ::: "memory")
; #define PG8_BAR __builtin_amdgcn_s_barrier()
; #define PG8_SCHED __builtin_amdgcn_sched_barrier(0)
; template <int EPI>
; __device__ __forceinline__ void gemm_phase(KP P, const bfu* __restrict__ A, const bfu* __restrict__ Bt, int K, int ntn, char* smem, const int wv) {
;     ...
;       PG8_STAGE(PG8_SB(0, 1), b2 + hstep);
;       PG8_WAIT_V(6); PG8_BAR; PG8_MMA(1, 1, At, B1); PG8_BAR;
;       PG8_LDB(B0, 1, 0); PG8_SCHED; PG8_LDA(At, 1, 0); PG8_STAGE(PG8_SA(0, 1), a2 + hstep);
;       PG8_WAIT_L(8); PG8_BAR; PG8_WAIT_L(0); PG8_MMA(0, 0, At, B0); PG8_BAR; PG8_SCHED;
;       PG8_LDB(B1, 1, 1); PG8_STAGE(PG8_SB(1, 0), b3);
;       PG8_BAR; PG8_WAIT_L(0); PG8_MMA(0, 1, At, B1); PG8_BAR;
;       PG8_LDA(At, 1, 1); PG8_STAGE(PG8_SA(1, 0), a3);
;       PG8_BAR; PG8_WAIT_L(0); PG8_MMA(1, 0, At, B0); PG8_BAR; PG8_SCHED;
	s_add_u32 s82, s26, 0x80000
	s_addc_u32 s83, s27, 0
	s_mov_b32 m0, s44
	v_lshl_add_u64 v[150:151], s[82:83], 0, v[130:131]
	global_load_lds_dwordx4 v[150:151], off
	v_lshl_add_u64 v[150:151], s[82:83], 0, v[132:133]
	s_mov_b32 m0, s45
	s_nop 0
	global_load_lds_dwordx4 v[150:151], off
	s_waitcnt vmcnt(6)
	s_barrier
	s_setprio 1
	v_mfma_f32_16x16x32_bf16 v[74:77], v[216:219], v[184:187], v[74:77]
	v_mfma_f32_16x16x32_bf16 v[78:81], v[224:227], v[184:187], v[78:81]
	v_mfma_f32_16x16x32_bf16 v[90:93], v[216:219], v[192:195], v[90:93]
	v_mfma_f32_16x16x32_bf16 v[94:97], v[224:227], v[192:195], v[94:97]
	v_mfma_f32_16x16x32_bf16 v[106:109], v[216:219], v[200:203], v[106:109]
	v_mfma_f32_16x16x32_bf16 v[110:113], v[224:227], v[200:203], v[110:113]
	v_mfma_f32_16x16x32_bf16 v[122:125], v[216:219], v[208:211], v[122:125]
	v_mfma_f32_16x16x32_bf16 v[126:129], v[224:227], v[208:211], v[126:129]
	v_mfma_f32_16x16x32_bf16 v[74:77], v[220:223], v[188:191], v[74:77]
	v_mfma_f32_16x16x32_bf16 v[78:81], v[228:231], v[188:191], v[78:81]
	v_mfma_f32_16x16x32_bf16 v[90:93], v[220:223], v[196:199], v[90:93]
	v_mfma_f32_16x16x32_bf16 v[94:97], v[228:231], v[196:199], v[94:97]
	v_mfma_f32_16x16x32_bf16 v[106:109], v[220:223], v[204:207], v[106:109]
	v_mfma_f32_16x16x32_bf16 v[110:113], v[228:231], v[204:207], v[110:113]
	v_mfma_f32_16x16x32_bf16 v[122:125], v[220:223], v[212:215], v[122:125]
	v_mfma_f32_16x16x32_bf16 v[126:129], v[228:231], v[212:215], v[126:129]
	s_setprio 0
	v_add_u32_e32 v0, s48, v145
	s_barrier
	ds_read_b128 v[150:153], v0
	ds_read_b128 v[154:157], v0 offset:1024
	ds_read_b128 v[158:161], v0 offset:2048
	ds_read_b128 v[180:183], v0 offset:3072
	s_add_u32 s30, s30, 0x80000
	s_addc_u32 s31, s31, 0
	s_mov_b32 m0, s46
	v_lshl_add_u64 v[216:217], s[30:31], 0, v[130:131]
	ds_read_b128 v[184:187], v149 offset:32768
	ds_read_b128 v[188:191], v149 offset:33792
	ds_read_b128 v[192:195], v149 offset:34816
	ds_read_b128 v[196:199], v149 offset:35840
	ds_read_b128 v[200:203], v149 offset:36864
	ds_read_b128 v[204:207], v149 offset:37888
	ds_read_b128 v[208:211], v149 offset:38912
	ds_read_b128 v[212:215], v149 offset:39936
	global_load_lds_dwordx4 v[216:217], off
	v_lshl_add_u64 v[216:217], s[30:31], 0, v[132:133]
	s_mov_b32 m0, s47
	s_nop 0
	global_load_lds_dwordx4 v[216:217], off
	s_waitcnt lgkmcnt(8)
	s_barrier
	s_waitcnt lgkmcnt(0)
	s_setprio 1
	s_waitcnt lgkmcnt(0)
	v_mfma_f32_16x16x32_bf16 v[2:5], v[150:153], v[184:187], v[2:5]
	v_mfma_f32_16x16x32_bf16 v[6:9], v[158:161], v[184:187], v[6:9]
	v_mfma_f32_16x16x32_bf16 v[18:21], v[150:153], v[192:195], v[18:21]
	v_mfma_f32_16x16x32_bf16 v[22:25], v[158:161], v[192:195], v[22:25]
	v_mfma_f32_16x16x32_bf16 v[34:37], v[150:153], v[200:203], v[34:37]
	v_mfma_f32_16x16x32_bf16 v[38:41], v[158:161], v[200:203], v[38:41]
	v_mfma_f32_16x16x32_bf16 v[50:53], v[150:153], v[208:211], v[50:53]
	v_mfma_f32_16x16x32_bf16 v[54:57], v[158:161], v[208:211], v[54:57]
	v_mfma_f32_16x16x32_bf16 v[2:5], v[154:157], v[188:191], v[2:5]
	v_mfma_f32_16x16x32_bf16 v[6:9], v[180:183], v[188:191], v[6:9]
	v_mfma_f32_16x16x32_bf16 v[18:21], v[154:157], v[196:199], v[18:21]
	v_mfma_f32_16x16x32_bf16 v[22:25], v[180:183], v[196:199], v[22:25]
	v_mfma_f32_16x16x32_bf16 v[34:37], v[154:157], v[204:207], v[34:37]
	v_mfma_f32_16x16x32_bf16 v[38:41], v[180:183], v[204:207], v[38:41]
	v_mfma_f32_16x16x32_bf16 v[50:53], v[154:157], v[212:215], v[50:53]
	v_mfma_f32_16x16x32_bf16 v[54:57], v[180:183], v[212:215], v[54:57]
	s_setprio 0
	s_barrier
	s_mov_b32 m0, s49
	v_add_u32_e32 v0, s60, v145
	v_lshl_add_u64 v[162:163], v[162:163], 0, s[90:91]
	ds_read_b128 v[216:219], v0
	ds_read_b128 v[220:223], v0 offset:1024
	ds_read_b128 v[224:227], v0 offset:2048
	ds_read_b128 v[228:231], v0 offset:3072
	global_load_lds_dwordx4 v[162:163], off
	v_lshl_add_u64 v[162:163], v[232:233], 0, s[90:91]
	s_mov_b32 m0, s50
	s_nop 0
	global_load_lds_dwordx4 v[162:163], off
	s_barrier
	s_waitcnt lgkmcnt(0)
	s_setprio 1
	s_waitcnt lgkmcnt(0)
	v_mfma_f32_16x16x32_bf16 v[10:13], v[216:219], v[184:187], v[10:13]
	v_mfma_f32_16x16x32_bf16 v[14:17], v[224:227], v[184:187], v[14:17]
	v_mfma_f32_16x16x32_bf16 v[26:29], v[216:219], v[192:195], v[26:29]
	v_mfma_f32_16x16x32_bf16 v[30:33], v[224:227], v[192:195], v[30:33]
	v_mfma_f32_16x16x32_bf16 v[42:45], v[216:219], v[200:203], v[42:45]
	v_mfma_f32_16x16x32_bf16 v[46:49], v[224:227], v[200:203], v[46:49]
	v_mfma_f32_16x16x32_bf16 v[58:61], v[216:219], v[208:211], v[58:61]
	v_mfma_f32_16x16x32_bf16 v[62:65], v[224:227], v[208:211], v[62:65]
	v_mfma_f32_16x16x32_bf16 v[10:13], v[220:223], v[188:191], v[10:13]
	v_mfma_f32_16x16x32_bf16 v[14:17], v[228:231], v[188:191], v[14:17]
	v_mfma_f32_16x16x32_bf16 v[26:29], v[220:223], v[196:199], v[26:29]
	v_mfma_f32_16x16x32_bf16 v[30:33], v[228:231], v[196:199], v[30:33]
	v_mfma_f32_16x16x32_bf16 v[42:45], v[220:223], v[204:207], v[42:45]
	v_mfma_f32_16x16x32_bf16 v[46:49], v[228:231], v[204:207], v[46:49]
	v_mfma_f32_16x16x32_bf16 v[58:61], v[220:223], v[212:215], v[58:61]
	v_mfma_f32_16x16x32_bf16 v[62:65], v[228:231], v[212:215], v[62:65]
	s_setprio 0
	s_mov_b32 m0, s51
	v_lshl_add_u64 v[162:163], v[234:235], 0, s[90:91]
	s_barrier
	ds_read_b128 v[184:187], v149 offset:49152
	ds_read_b128 v[188:191], v149 offset:50176
	ds_read_b128 v[192:195], v149 offset:51200
	ds_read_b128 v[196:199], v149 offset:52224
	ds_read_b128 v[200:203], v149 offset:53248
	ds_read_b128 v[204:207], v149 offset:54272
	ds_read_b128 v[208:211], v149 offset:55296
	ds_read_b128 v[212:215], v149 offset:56320
	global_load_lds_dwordx4 v[162:163], off
	v_lshl_add_u64 v[162:163], v[236:237], 0, s[90:91]
	s_mov_b32 m0, s52
	s_nop 0
	global_load_lds_dwordx4 v[162:163], off
	s_barrier
; #define PG8_STAGE(bufoff, gbase) do { _Pragma("unroll") for (int _i = 0; _i < 2; ++_i) \
;     __builtin_amdgcn_global_load_lds((const unsigned*)((const char*)(gbase) + voff[_i]), (LAS unsigned*)(lds + (bufoff) + ldsw + _i * 8192), 16, 0, 0); } while (0)
; #define PG8_MMA(ai, bj, At, Bt_) do { __builtin_amdgcn_s_setprio(1); _Pragma("unroll") for (int m = 0; m < 4; ++m) _Pragma("unroll") for (int n = 0; n < 2; ++n) _Pragma("unroll") for (int k = 0; k < 2; ++k) \
;     acc[ai][bj][m][n] = __builtin_amdgcn_mfma_f32_16x16x32_bf16(Bt_[n][k], At[m][k], acc[ai][bj][m][n], 0, 0, 0); __builtin_amdgcn_s_setprio(0); } while (0)
; #define PG8_WAIT_V(n) asm volatile("s_waitcnt vmcnt(" #n ")" ::: "memory")
; #define PG8_WAIT_L(n) asm volatile("s_waitcnt lgkmcnt(" #n ")" ::: "memory")
; #define PG8_BAR __builtin_amdgcn_s_barrier()
; #define PG8_SCHED __builtin_amdgcn_sched_barrier(0)
; template <int EPI>
; __device__ __forceinline__ void gemm_epilogue(KP P, f32x4 (&acc)[2][2][4][2], int brow, int bcol, int wr, int wc, int fr_, int fq_, const float* sRu) {
;     ...
;   } else if (EPI == EPI_OUTPROJ || EPI == EPI_RES) {
;     bfu* xo = (bfu*)(P->ws + WS_XR) + (size_t)brow * D + bcol;
; #pragma unroll
;     for (int ai = 0; ai < 2; ++ai)
; #pragma unroll
;       for (int m = 0; m < 4; ++m) {
;         __builtin_amdgcn_sched_barrier(0);
;         unsigned lr = lrow0 + ai * 128 + m * 16;
;         unsigned o = lr * D + lcol0;
;         float rsd = 1.f;
;         if (EPI == EPI_OUTPROJ) rsd = sRu[lr];
; #pragma unroll
;         for (int bj = 0; bj < 2; ++bj)
; #pragma unroll
;           for (int n = 0; n < 2; ++n) {
;             f32x4 v = acc[ai][bj][m][n] * rsd;
;             uint2 pk; pk.x = cvt_pk_bf16(v[0], v[1]); pk.y = cvt_pk_bf16(v[2], v[3]);
;             *(uint2*)(xo + o + bj * 128 + n * 16) = pk;
;           }
;       }
; template <int EPI>
; __device__ __forceinline__ void gemm_phase(KP P, const bfu* __restrict__ A, const bfu* __restrict__ Bt, int K, int ntn, char* smem, const int wv) {
;     ...
;       PG8_BAR; PG8_WAIT_L(0); PG8_MMA(1, 0, At, B0); PG8_BAR; PG8_SCHED;
;       PG8_STAGE(PG8_SB(1, 1), b3 + hstep);
;       PG8_WAIT_V(6); PG8_BAR; PG8_MMA(1, 1, At, B1); PG8_BAR;
;     }
	s_waitcnt lgkmcnt(0)
	s_setprio 1
	s_waitcnt lgkmcnt(0)
	v_mfma_f32_16x16x32_bf16 v[66:69], v[150:153], v[184:187], v[66:69]
	v_mfma_f32_16x16x32_bf16 v[70:73], v[158:161], v[184:187], v[70:73]
	v_mfma_f32_16x16x32_bf16 v[82:85], v[150:153], v[192:195], v[82:85]
	v_mfma_f32_16x16x32_bf16 v[86:89], v[158:161], v[192:195], v[86:89]
	v_mfma_f32_16x16x32_bf16 v[98:101], v[150:153], v[200:203], v[98:101]
	v_mfma_f32_16x16x32_bf16 v[102:105], v[158:161], v[200:203], v[102:105]
	v_mfma_f32_16x16x32_bf16 v[114:117], v[150:153], v[208:211], v[114:117]
	v_mfma_f32_16x16x32_bf16 v[118:121], v[158:161], v[208:211], v[118:121]
	v_mfma_f32_16x16x32_bf16 v[66:69], v[154:157], v[188:191], v[66:69]
	v_mfma_f32_16x16x32_bf16 v[70:73], v[180:183], v[188:191], v[70:73]
	v_mfma_f32_16x16x32_bf16 v[82:85], v[154:157], v[196:199], v[82:85]
	v_mfma_f32_16x16x32_bf16 v[86:89], v[180:183], v[196:199], v[86:89]
	v_mfma_f32_16x16x32_bf16 v[98:101], v[154:157], v[204:207], v[98:101]
	v_mfma_f32_16x16x32_bf16 v[102:105], v[180:183], v[204:207], v[102:105]
	v_mfma_f32_16x16x32_bf16 v[114:117], v[154:157], v[212:215], v[114:117]
	v_mfma_f32_16x16x32_bf16 v[118:121], v[180:183], v[212:215], v[118:121]
	s_setprio 0
	s_barrier
	s_add_u32 s26, s26, 0x80080
	s_addc_u32 s27, s27, 0
	s_mov_b32 m0, s62
	v_lshl_add_u64 v[150:151], s[26:27], 0, v[130:131]
	global_load_lds_dwordx4 v[150:151], off
	v_lshl_add_u64 v[150:151], s[26:27], 0, v[132:133]
	s_mov_b32 m0, s67
	s_nop 0
	global_load_lds_dwordx4 v[150:151], off
	s_waitcnt vmcnt(6)
	s_barrier
	s_setprio 1
	v_mfma_f32_16x16x32_bf16 v[74:77], v[216:219], v[184:187], v[74:77]
	v_mfma_f32_16x16x32_bf16 v[78:81], v[224:227], v[184:187], v[78:81]
	v_mfma_f32_16x16x32_bf16 v[90:93], v[216:219], v[192:195], v[90:93]
	v_mfma_f32_16x16x32_bf16 v[94:97], v[224:227], v[192:195], v[94:97]
	v_mfma_f32_16x16x32_bf16 v[106:109], v[216:219], v[200:203], v[106:109]
	v_mfma_f32_16x16x32_bf16 v[110:113], v[224:227], v[200:203], v[110:113]
	v_mfma_f32_16x16x32_bf16 v[122:125], v[216:219], v[208:211], v[122:125]
	v_mfma_f32_16x16x32_bf16 v[126:129], v[224:227], v[208:211], v[126:129]
	v_mfma_f32_16x16x32_bf16 v[74:77], v[220:223], v[188:191], v[74:77]
	v_mfma_f32_16x16x32_bf16 v[78:81], v[228:231], v[188:191], v[78:81]
	v_mfma_f32_16x16x32_bf16 v[90:93], v[220:223], v[196:199], v[90:93]
	v_mfma_f32_16x16x32_bf16 v[94:97], v[228:231], v[196:199], v[94:97]
	v_mfma_f32_16x16x32_bf16 v[106:109], v[220:223], v[204:207], v[106:109]
	v_mfma_f32_16x16x32_bf16 v[110:113], v[228:231], v[204:207], v[110:113]
	v_mfma_f32_16x16x32_bf16 v[122:125], v[220:223], v[212:215], v[122:125]
	v_mfma_f32_16x16x32_bf16 v[126:129], v[228:231], v[212:215], v[126:129]
	s_setprio 0
	s_add_i32 s80, s80, 2
	s_add_u32 s24, s24, 0x100
	s_addc_u32 s25, s25, 0
	s_cmp_gt_u32 s80, 29
	s_barrier
	s_cbranch_scc0 .LBB0_310
	s_lshl_b32 s24, s22, 8
	s_ashr_i32 s25, s24, 31
	s_lshl_b32 s20, s20, 8
	s_lshl_b64 s[24:25], s[24:25], 11
	s_add_u32 s5, s6, s24
	s_addc_u32 s11, s7, s25
	s_ashr_i32 s21, s20, 31
	s_lshl_b64 s[20:21], s[20:21], 1
	v_mov_b32_e32 v0, v142
	v_mov_b32_e32 v138, v143
	s_add_u32 s20, s5, s20
	s_addc_u32 s21, s11, s21
	v_add_u32_e32 v0, s94, v0
	v_lshlrev_b32_e32 v139, 2, v138
	v_lshl_add_u32 v150, v0, 2, s74
	ds_read_b32 v138, v150
	v_lshlrev_b32_e32 v0, 10, v0
	v_readlane_b32 s5, v241, 20
	s_waitcnt lgkmcnt(0)
	v_pk_mul_f32 v[4:5], v[4:5], v[138:139] op_sel_hi:[1,0]
	v_add3_u32 v0, v139, s5, v0
	v_and_b32_e32 v208, 1, v143
	v_mul_u32_u24_e32 v208, 12, v208
	v_add_u32_e32 v0, v0, v208
	v_pk_mul_f32 v[2:3], v[2:3], v[138:139] op_sel_hi:[1,0]
	v_lshl_add_u64 v[140:141], v[0:1], 1, s[20:21]
	v_cvt_pk_bf16_f32 v200, v2, v3
	v_cvt_pk_bf16_f32 v201, v4, v5
	v_pk_mul_f32 v[4:5], v[6:7], v[138:139] op_sel_hi:[1,0]
	v_pk_mul_f32 v[2:3], v[8:9], v[138:139] op_sel_hi:[1,0]
	v_cvt_pk_bf16_f32 v202, v4, v5
	s_nop 0
	v_cvt_pk_bf16_f32 v203, v2, v3
	s_nop 1
	v_permlane16_swap_b32_e32 v200, v202
	v_permlane16_swap_b32_e32 v201, v203
	global_store_dwordx4 v[140:141], v[200:203], off
	v_pk_mul_f32 v[4:5], v[10:11], v[138:139] op_sel_hi:[1,0]
	v_pk_mul_f32 v[2:3], v[12:13], v[138:139] op_sel_hi:[1,0]
	v_cvt_pk_bf16_f32 v204, v4, v5
	s_nop 0
	v_cvt_pk_bf16_f32 v205, v2, v3
	v_pk_mul_f32 v[2:3], v[16:17], v[138:139] op_sel_hi:[1,0]
	v_pk_mul_f32 v[4:5], v[14:15], v[138:139] op_sel_hi:[1,0]
	s_nop 0
	v_cvt_pk_bf16_f32 v206, v4, v5
	v_cvt_pk_bf16_f32 v207, v2, v3
	s_nop 1
	v_permlane16_swap_b32_e32 v204, v206
	v_permlane16_swap_b32_e32 v205, v207
	global_store_dwordx4 v[140:141], v[204:207], off offset:256
	ds_read_b32 v2, v150 offset:64
	v_add_u32_e32 v4, 0x4000, v0
	v_mov_b32_e32 v5, v1
	v_lshl_add_u64 v[4:5], v[4:5], 1, s[20:21]
	s_waitcnt lgkmcnt(0)
	v_pk_mul_f32 v[8:9], v[18:19], v[2:3] op_sel_hi:[1,0]
	v_pk_mul_f32 v[6:7], v[20:21], v[2:3] op_sel_hi:[1,0]
	v_cvt_pk_bf16_f32 v200, v8, v9
	s_nop 0
	v_cvt_pk_bf16_f32 v201, v6, v7
	v_pk_mul_f32 v[8:9], v[22:23], v[2:3] op_sel_hi:[1,0]
	v_pk_mul_f32 v[6:7], v[24:25], v[2:3] op_sel_hi:[1,0]
	v_cvt_pk_bf16_f32 v202, v8, v9
	s_nop 0
	v_cvt_pk_bf16_f32 v203, v6, v7
	s_nop 1
	v_permlane16_swap_b32_e32 v200, v202
	v_permlane16_swap_b32_e32 v201, v203
	global_store_dwordx4 v[4:5], v[200:203], off
	v_pk_mul_f32 v[6:7], v[28:29], v[2:3] op_sel_hi:[1,0]
	v_pk_mul_f32 v[8:9], v[26:27], v[2:3] op_sel_hi:[1,0]
	s_nop 0
	v_cvt_pk_bf16_f32 v204, v8, v9
	v_cvt_pk_bf16_f32 v205, v6, v7
	v_pk_mul_f32 v[6:7], v[32:33], v[2:3] op_sel_hi:[1,0]
	v_pk_mul_f32 v[2:3], v[30:31], v[2:3] op_sel_hi:[1,0]
	v_cvt_pk_bf16_f32 v206, v2, v3
	v_cvt_pk_bf16_f32 v207, v6, v7
	s_nop 1
	v_permlane16_swap_b32_e32 v204, v206
	v_permlane16_swap_b32_e32 v205, v207
	global_store_dwordx4 v[4:5], v[204:207], off offset:256
	ds_read_b32 v2, v150 offset:128
	v_add_u32_e32 v4, 0x8000, v0
	v_mov_b32_e32 v5, v1
	v_lshl_add_u64 v[4:5], v[4:5], 1, s[20:21]
	s_waitcnt lgkmcnt(0)
; template <int EPI>
; __device__ __forceinline__ void gemm_epilogue(KP P, f32x4 (&acc)[2][2][4][2], int brow, int bcol, int wr, int wc, int fr_, int fq_, const float* sRu) {
;     ...
;   } else if (EPI == EPI_OUTPROJ || EPI == EPI_RES) {
;     bfu* xo = (bfu*)(P->ws + WS_XR) + (size_t)brow * D + bcol;
; #pragma unroll
;     for (int ai = 0; ai < 2; ++ai)
; #pragma unroll
;       for (int m = 0; m < 4; ++m) {
;         __builtin_amdgcn_sched_barrier(0);
;         unsigned lr = lrow0 + ai * 128 + m * 16;
;         unsigned o = lr * D + lcol0;
;         float rsd = 1.f;
;         if (EPI == EPI_OUTPROJ) rsd = sRu[lr];
; #pragma unroll
;         for (int bj = 0; bj < 2; ++bj)
; #pragma unroll
;           for (int n = 0; n < 2; ++n) {
;             f32x4 v = acc[ai][bj][m][n] * rsd;
;             uint2 pk; pk.x = cvt_pk_bf16(v[0], v[1]); pk.y = cvt_pk_bf16(v[2], v[3]);
;             *(uint2*)(xo + o + bj * 128 + n * 16) = pk;
;           }
;       }
; template <int EPI>
; __device__ __forceinline__ void gemm_phase(KP P, const bfu* __restrict__ A, const bfu* __restrict__ Bt, int K, int ntn, char* smem, const int wv) {
;     ...
;     if (!has_next) break;
	v_pk_mul_f32 v[8:9], v[34:35], v[2:3] op_sel_hi:[1,0]
	v_pk_mul_f32 v[6:7], v[36:37], v[2:3] op_sel_hi:[1,0]
	v_cvt_pk_bf16_f32 v200, v8, v9
	s_nop 0
	v_cvt_pk_bf16_f32 v201, v6, v7
	v_pk_mul_f32 v[8:9], v[38:39], v[2:3] op_sel_hi:[1,0]
	v_pk_mul_f32 v[6:7], v[40:41], v[2:3] op_sel_hi:[1,0]
	v_cvt_pk_bf16_f32 v202, v8, v9
	s_nop 0
	v_cvt_pk_bf16_f32 v203, v6, v7
	s_nop 1
	v_permlane16_swap_b32_e32 v200, v202
	v_permlane16_swap_b32_e32 v201, v203
	global_store_dwordx4 v[4:5], v[200:203], off
	v_pk_mul_f32 v[6:7], v[44:45], v[2:3] op_sel_hi:[1,0]
	v_pk_mul_f32 v[8:9], v[42:43], v[2:3] op_sel_hi:[1,0]
	s_nop 0
	v_cvt_pk_bf16_f32 v204, v8, v9
	v_cvt_pk_bf16_f32 v205, v6, v7
	v_pk_mul_f32 v[6:7], v[48:49], v[2:3] op_sel_hi:[1,0]
	v_pk_mul_f32 v[2:3], v[46:47], v[2:3] op_sel_hi:[1,0]
	v_cvt_pk_bf16_f32 v206, v2, v3
	v_cvt_pk_bf16_f32 v207, v6, v7
	s_nop 1
	v_permlane16_swap_b32_e32 v204, v206
	v_permlane16_swap_b32_e32 v205, v207
	global_store_dwordx4 v[4:5], v[204:207], off offset:256
	ds_read_b32 v2, v150 offset:192
	v_add_u32_e32 v4, 0xc000, v0
	v_mov_b32_e32 v5, v1
	v_lshl_add_u64 v[4:5], v[4:5], 1, s[20:21]
	s_waitcnt lgkmcnt(0)
	v_pk_mul_f32 v[8:9], v[50:51], v[2:3] op_sel_hi:[1,0]
	v_pk_mul_f32 v[6:7], v[52:53], v[2:3] op_sel_hi:[1,0]
	v_cvt_pk_bf16_f32 v200, v8, v9
	s_nop 0
	v_cvt_pk_bf16_f32 v201, v6, v7
	v_pk_mul_f32 v[8:9], v[54:55], v[2:3] op_sel_hi:[1,0]
	v_pk_mul_f32 v[6:7], v[56:57], v[2:3] op_sel_hi:[1,0]
	v_cvt_pk_bf16_f32 v202, v8, v9
	s_nop 0
	v_cvt_pk_bf16_f32 v203, v6, v7
	s_nop 1
	v_permlane16_swap_b32_e32 v200, v202
	v_permlane16_swap_b32_e32 v201, v203
	global_store_dwordx4 v[4:5], v[200:203], off
	v_pk_mul_f32 v[6:7], v[60:61], v[2:3] op_sel_hi:[1,0]
	v_pk_mul_f32 v[8:9], v[58:59], v[2:3] op_sel_hi:[1,0]
	s_nop 0
	v_cvt_pk_bf16_f32 v204, v8, v9
	v_cvt_pk_bf16_f32 v205, v6, v7
	v_pk_mul_f32 v[6:7], v[64:65], v[2:3] op_sel_hi:[1,0]
	v_pk_mul_f32 v[2:3], v[62:63], v[2:3] op_sel_hi:[1,0]
	v_cvt_pk_bf16_f32 v206, v2, v3
	v_cvt_pk_bf16_f32 v207, v6, v7
	s_nop 1
	v_permlane16_swap_b32_e32 v204, v206
	v_permlane16_swap_b32_e32 v205, v207
	global_store_dwordx4 v[4:5], v[204:207], off offset:256
	ds_read_b32 v2, v150 offset:512
	v_add_u32_e32 v4, 0x20000, v0
	v_mov_b32_e32 v5, v1
	v_lshl_add_u64 v[4:5], v[4:5], 1, s[20:21]
	s_waitcnt lgkmcnt(0)
	v_pk_mul_f32 v[8:9], v[66:67], v[2:3] op_sel_hi:[1,0]
	v_pk_mul_f32 v[6:7], v[68:69], v[2:3] op_sel_hi:[1,0]
	v_cvt_pk_bf16_f32 v200, v8, v9
	s_nop 0
	v_cvt_pk_bf16_f32 v201, v6, v7
	v_pk_mul_f32 v[8:9], v[70:71], v[2:3] op_sel_hi:[1,0]
	v_pk_mul_f32 v[6:7], v[72:73], v[2:3] op_sel_hi:[1,0]
	v_cvt_pk_bf16_f32 v202, v8, v9
	s_nop 0
	v_cvt_pk_bf16_f32 v203, v6, v7
	s_nop 1
	v_permlane16_swap_b32_e32 v200, v202
	v_permlane16_swap_b32_e32 v201, v203
	global_store_dwordx4 v[4:5], v[200:203], off
	v_pk_mul_f32 v[6:7], v[76:77], v[2:3] op_sel_hi:[1,0]
	v_pk_mul_f32 v[8:9], v[74:75], v[2:3] op_sel_hi:[1,0]
	s_nop 0
	v_cvt_pk_bf16_f32 v204, v8, v9
	v_cvt_pk_bf16_f32 v205, v6, v7
	v_pk_mul_f32 v[6:7], v[80:81], v[2:3] op_sel_hi:[1,0]
	v_pk_mul_f32 v[2:3], v[78:79], v[2:3] op_sel_hi:[1,0]
	v_cvt_pk_bf16_f32 v206, v2, v3
	v_cvt_pk_bf16_f32 v207, v6, v7
	s_nop 1
	v_permlane16_swap_b32_e32 v204, v206
	v_permlane16_swap_b32_e32 v205, v207
	global_store_dwordx4 v[4:5], v[204:207], off offset:256
	ds_read_b32 v2, v150 offset:576
	v_add_u32_e32 v4, 0x24000, v0
	v_mov_b32_e32 v5, v1
	v_lshl_add_u64 v[4:5], v[4:5], 1, s[20:21]
	s_waitcnt lgkmcnt(0)
	v_pk_mul_f32 v[8:9], v[82:83], v[2:3] op_sel_hi:[1,0]
	v_pk_mul_f32 v[6:7], v[84:85], v[2:3] op_sel_hi:[1,0]
	v_cvt_pk_bf16_f32 v200, v8, v9
	s_nop 0
	v_cvt_pk_bf16_f32 v201, v6, v7
	v_pk_mul_f32 v[8:9], v[86:87], v[2:3] op_sel_hi:[1,0]
	v_pk_mul_f32 v[6:7], v[88:89], v[2:3] op_sel_hi:[1,0]
	v_cvt_pk_bf16_f32 v202, v8, v9
	s_nop 0
	v_cvt_pk_bf16_f32 v203, v6, v7
	s_nop 1
	v_permlane16_swap_b32_e32 v200, v202
	v_permlane16_swap_b32_e32 v201, v203
	global_store_dwordx4 v[4:5], v[200:203], off
	v_pk_mul_f32 v[6:7], v[92:93], v[2:3] op_sel_hi:[1,0]
	v_pk_mul_f32 v[8:9], v[90:91], v[2:3] op_sel_hi:[1,0]
	s_nop 0
	v_cvt_pk_bf16_f32 v204, v8, v9
	v_cvt_pk_bf16_f32 v205, v6, v7
	v_pk_mul_f32 v[6:7], v[96:97], v[2:3] op_sel_hi:[1,0]
	v_pk_mul_f32 v[2:3], v[94:95], v[2:3] op_sel_hi:[1,0]
	v_cvt_pk_bf16_f32 v206, v2, v3
	v_cvt_pk_bf16_f32 v207, v6, v7
	s_nop 1
	v_permlane16_swap_b32_e32 v204, v206
	v_permlane16_swap_b32_e32 v205, v207
	global_store_dwordx4 v[4:5], v[204:207], off offset:256
	ds_read_b32 v2, v150 offset:640
	v_add_u32_e32 v4, 0x28000, v0
	v_mov_b32_e32 v5, v1
	v_lshl_add_u64 v[4:5], v[4:5], 1, s[20:21]
	s_waitcnt lgkmcnt(0)
	v_pk_mul_f32 v[8:9], v[98:99], v[2:3] op_sel_hi:[1,0]
	v_pk_mul_f32 v[6:7], v[100:101], v[2:3] op_sel_hi:[1,0]
	v_cvt_pk_bf16_f32 v200, v8, v9
	s_nop 0
	v_cvt_pk_bf16_f32 v201, v6, v7
	v_pk_mul_f32 v[8:9], v[102:103], v[2:3] op_sel_hi:[1,0]
	v_pk_mul_f32 v[6:7], v[104:105], v[2:3] op_sel_hi:[1,0]
	v_cvt_pk_bf16_f32 v202, v8, v9
	s_nop 0
	v_cvt_pk_bf16_f32 v203, v6, v7
	s_nop 1
	v_permlane16_swap_b32_e32 v200, v202
	v_permlane16_swap_b32_e32 v201, v203
	global_store_dwordx4 v[4:5], v[200:203], off
	v_pk_mul_f32 v[6:7], v[108:109], v[2:3] op_sel_hi:[1,0]
	v_pk_mul_f32 v[8:9], v[106:107], v[2:3] op_sel_hi:[1,0]
	s_nop 0
	v_cvt_pk_bf16_f32 v204, v8, v9
	v_cvt_pk_bf16_f32 v205, v6, v7
	v_pk_mul_f32 v[6:7], v[112:113], v[2:3] op_sel_hi:[1,0]
	v_pk_mul_f32 v[2:3], v[110:111], v[2:3] op_sel_hi:[1,0]
	v_cvt_pk_bf16_f32 v206, v2, v3
	v_cvt_pk_bf16_f32 v207, v6, v7
	s_nop 1
	v_permlane16_swap_b32_e32 v204, v206
	v_permlane16_swap_b32_e32 v205, v207
	global_store_dwordx4 v[4:5], v[204:207], off offset:256
	ds_read_b32 v2, v150 offset:704
	v_add_u32_e32 v0, 0x2c000, v0
	v_lshl_add_u64 v[4:5], v[0:1], 1, s[20:21]
	s_mov_b64 s[20:21], -1
	s_and_b64 vcc, exec, s[28:29]
	s_waitcnt lgkmcnt(0)
	v_pk_mul_f32 v[8:9], v[114:115], v[2:3] op_sel_hi:[1,0]
	v_pk_mul_f32 v[6:7], v[116:117], v[2:3] op_sel_hi:[1,0]
	v_cvt_pk_bf16_f32 v200, v8, v9
	s_nop 0
	v_cvt_pk_bf16_f32 v201, v6, v7
	v_pk_mul_f32 v[8:9], v[118:119], v[2:3] op_sel_hi:[1,0]
	v_pk_mul_f32 v[6:7], v[120:121], v[2:3] op_sel_hi:[1,0]
	v_cvt_pk_bf16_f32 v202, v8, v9
	s_nop 0
	v_cvt_pk_bf16_f32 v203, v6, v7
	s_nop 1
	v_permlane16_swap_b32_e32 v200, v202
	v_permlane16_swap_b32_e32 v201, v203
	global_store_dwordx4 v[4:5], v[200:203], off
	v_pk_mul_f32 v[6:7], v[124:125], v[2:3] op_sel_hi:[1,0]
	v_pk_mul_f32 v[8:9], v[122:123], v[2:3] op_sel_hi:[1,0]
	s_nop 0
	v_cvt_pk_bf16_f32 v204, v8, v9
	v_cvt_pk_bf16_f32 v205, v6, v7
	v_pk_mul_f32 v[6:7], v[128:129], v[2:3] op_sel_hi:[1,0]
	v_pk_mul_f32 v[2:3], v[126:127], v[2:3] op_sel_hi:[1,0]
	v_cvt_pk_bf16_f32 v206, v2, v3
	v_cvt_pk_bf16_f32 v207, v6, v7
	s_nop 1
	v_permlane16_swap_b32_e32 v204, v206
	v_permlane16_swap_b32_e32 v205, v207
	global_store_dwordx4 v[4:5], v[204:207], off offset:256
	s_cbranch_vccz .LBB0_306
; template <int EPI>
; __device__ __forceinline__ void gemm_acc_init(KP P, f32x4 (&acc)[2][2][4][2], int brow, int bcol, int wr, int wc, int fr_, int fq_, const float* sRu) {
;   if (EPI == EPI_OUTPROJ || EPI == EPI_RES) {
;     int fr = fr_, fq = fq_;
;     asm volatile("" : "+v"(fr), "+v"(fq));
;     const float* xin = (brow < MP ? P->in[0] + (size_t)brow * D : P->in[1] + (size_t)(brow - MP) * D) + bcol;
;     const bfu* xrb = (const bfu*)(P->ws + WS_XR) + (size_t)brow * D + bcol;
; #pragma unroll
;     for (int ai = 0; ai < 2; ++ai)
; #pragma unroll
;       for (int m = 0; m < 4; ++m) {
;         __builtin_amdgcn_sched_barrier(0);
;         unsigned lr = ai * 128 + wr * 64 + m * 16 + fr;
;         unsigned o = lr * D + wc * 32 + fq * 4;
;         float sc = 1.f;
;         if (EPI == EPI_OUTPROJ) sc = 1.f / sRu[lr];
; #pragma unroll
;         for (int bj = 0; bj < 2; ++bj)
; #pragma unroll
;           for (int n = 0; n < 2; ++n) {
;             if (EPI == EPI_RES) acc[ai][bj][m][n] = bf4_to_f32(*(const uint2*)(xrb + o + bj * 128 + n * 16));
;             else acc[ai][bj][m][n] = *(const f32x4*)(xin + o + bj * 128 + n * 16) * sc;
;           }
;       }
; template <int EPI>
; __device__ __forceinline__ void gemm_phase(KP P, const bfu* __restrict__ A, const bfu* __restrict__ Bt, int K, int ntn, char* smem, const int wv) {
;     ...
;     if (!has_next) break;
;     sRu += 256;
;     gemm_acc_init<EPI>(P, acc, npm * 256, npn * 256, wr, wc, fr, fq, sRu);
;     ctile = ntile; cpm = npm; cpn = npn; cA = nA; cB = nB;
	s_lshl_b32 s11, s4, 8
	s_add_i32 s5, s74, 0x400
	s_lshl_b32 s20, s10, 8
	s_add_i32 s21, s11, 0xffff0000
	s_ashr_i32 s22, s11, 31
	s_cmpk_lt_i32 s4, 0x100
	s_cselect_b32 s24, s11, s21
	s_cselect_b32 s11, 0, 8
	s_cselect_b32 s25, s22, 0
	s_add_u32 s26, s0, s11
	v_mov_b32_e32 v0, v143
	v_mov_b32_e32 v2, v142
	s_addc_u32 s27, s1, 0
	s_load_dwordx2 s[26:27], s[26:27], 0x0
	s_lshl_b64 s[24:25], s[24:25], 12
	v_add_u32_e32 v2, s94, v2
	v_lshlrev_b32_e32 v0, 2, v0
	s_waitcnt lgkmcnt(0)
	s_add_u32 s11, s26, s24
	s_addc_u32 s22, s27, s25
	s_ashr_i32 s21, s20, 31
	s_lshl_b64 s[20:21], s[20:21], 2
	s_add_u32 s20, s11, s20
	s_addc_u32 s21, s22, s21
	v_lshl_add_u32 v114, v2, 2, s74
	v_lshlrev_b32_e32 v3, 10, v2
	v_readlane_b32 s11, v241, 20
	s_nop 1
	v_add3_u32 v0, v0, s11, v3
	ds_read_b32 v200, v114 offset:1024
	ds_read_b32 v201, v114 offset:1088
	ds_read_b32 v202, v114 offset:1152
	ds_read_b32 v203, v114 offset:1216
	ds_read_b32 v204, v114 offset:1536
	ds_read_b32 v205, v114 offset:1600
	ds_read_b32 v206, v114 offset:1664
	ds_read_b32 v207, v114 offset:1728
	v_lshl_add_u64 v[184:185], v[0:1], 2, s[20:21]
	global_load_dwordx4 v[2:5], v[184:185], off
	global_load_dwordx4 v[6:9], v[184:185], off offset:64
	global_load_dwordx4 v[10:13], v[184:185], off offset:512
	global_load_dwordx4 v[14:17], v[184:185], off offset:576
	v_add_u32_e32 v186, 0x4000, v0
	v_mov_b32_e32 v187, v1
	v_lshl_add_u64 v[186:187], v[186:187], 2, s[20:21]
	global_load_dwordx4 v[18:21], v[186:187], off
	global_load_dwordx4 v[22:25], v[186:187], off offset:64
	global_load_dwordx4 v[26:29], v[186:187], off offset:512
	global_load_dwordx4 v[30:33], v[186:187], off offset:576
	v_add_u32_e32 v188, 0x8000, v0
	v_mov_b32_e32 v189, v1
	v_lshl_add_u64 v[188:189], v[188:189], 2, s[20:21]
	global_load_dwordx4 v[34:37], v[188:189], off
	global_load_dwordx4 v[38:41], v[188:189], off offset:64
	global_load_dwordx4 v[42:45], v[188:189], off offset:512
	global_load_dwordx4 v[46:49], v[188:189], off offset:576
	v_add_u32_e32 v190, 0xc000, v0
	v_mov_b32_e32 v191, v1
	v_lshl_add_u64 v[190:191], v[190:191], 2, s[20:21]
	global_load_dwordx4 v[50:53], v[190:191], off
	global_load_dwordx4 v[54:57], v[190:191], off offset:64
	global_load_dwordx4 v[58:61], v[190:191], off offset:512
	global_load_dwordx4 v[62:65], v[190:191], off offset:576
	v_add_u32_e32 v192, 0x20000, v0
	v_mov_b32_e32 v193, v1
	v_lshl_add_u64 v[192:193], v[192:193], 2, s[20:21]
	global_load_dwordx4 v[66:69], v[192:193], off
	global_load_dwordx4 v[70:73], v[192:193], off offset:64
	global_load_dwordx4 v[74:77], v[192:193], off offset:512
	global_load_dwordx4 v[78:81], v[192:193], off offset:576
	v_add_u32_e32 v194, 0x24000, v0
	v_mov_b32_e32 v195, v1
	v_lshl_add_u64 v[194:195], v[194:195], 2, s[20:21]
	global_load_dwordx4 v[82:85], v[194:195], off
	global_load_dwordx4 v[86:89], v[194:195], off offset:64
	global_load_dwordx4 v[90:93], v[194:195], off offset:512
	global_load_dwordx4 v[94:97], v[194:195], off offset:576
	v_add_u32_e32 v196, 0x28000, v0
	v_mov_b32_e32 v197, v1
	v_lshl_add_u64 v[196:197], v[196:197], 2, s[20:21]
	global_load_dwordx4 v[98:101], v[196:197], off
	global_load_dwordx4 v[102:105], v[196:197], off offset:64
	global_load_dwordx4 v[106:109], v[196:197], off offset:512
	global_load_dwordx4 v[110:113], v[196:197], off offset:576
	v_add_u32_e32 v198, 0x2c000, v0
	v_mov_b32_e32 v199, v1
	v_lshl_add_u64 v[198:199], v[198:199], 2, s[20:21]
	global_load_dwordx4 v[114:117], v[198:199], off
	global_load_dwordx4 v[118:121], v[198:199], off offset:64
	global_load_dwordx4 v[122:125], v[198:199], off offset:512
	global_load_dwordx4 v[126:129], v[198:199], off offset:576
	s_waitcnt lgkmcnt(0)
	v_div_scale_f32 v208, s[24:25], v200, v200, 1.0
	v_rcp_f32_e32 v209, v208
	s_nop 0
	v_fma_f32 v210, -v208, v209, 1.0
	v_fmac_f32_e32 v209, v210, v209
	v_div_scale_f32 v210, vcc, 1.0, v200, 1.0
	v_mul_f32_e32 v211, v210, v209
	v_fma_f32 v212, -v208, v211, v210
	v_fmac_f32_e32 v211, v212, v209
	v_fma_f32 v208, -v208, v211, v210
	v_div_fmas_f32 v208, v208, v209, v211
	v_div_fixup_f32 v214, v208, v200, 1.0
	v_div_scale_f32 v208, s[24:25], v201, v201, 1.0
	v_rcp_f32_e32 v209, v208
	s_nop 0
	v_fma_f32 v210, -v208, v209, 1.0
	v_fmac_f32_e32 v209, v210, v209
	v_div_scale_f32 v210, vcc, 1.0, v201, 1.0
	v_mul_f32_e32 v211, v210, v209
	v_fma_f32 v212, -v208, v211, v210
	v_fmac_f32_e32 v211, v212, v209
	v_fma_f32 v208, -v208, v211, v210
	v_div_fmas_f32 v208, v208, v209, v211
	v_div_fixup_f32 v216, v208, v201, 1.0
	v_div_scale_f32 v208, s[24:25], v202, v202, 1.0
	v_rcp_f32_e32 v209, v208
	s_nop 0
	v_fma_f32 v210, -v208, v209, 1.0
	v_fmac_f32_e32 v209, v210, v209
	v_div_scale_f32 v210, vcc, 1.0, v202, 1.0
	v_mul_f32_e32 v211, v210, v209
	v_fma_f32 v212, -v208, v211, v210
	v_fmac_f32_e32 v211, v212, v209
	v_fma_f32 v208, -v208, v211, v210
	v_div_fmas_f32 v208, v208, v209, v211
	v_div_fixup_f32 v218, v208, v202, 1.0
	v_div_scale_f32 v208, s[24:25], v203, v203, 1.0
	v_rcp_f32_e32 v209, v208
	s_nop 0
	v_fma_f32 v210, -v208, v209, 1.0
	v_fmac_f32_e32 v209, v210, v209
	v_div_scale_f32 v210, vcc, 1.0, v203, 1.0
	v_mul_f32_e32 v211, v210, v209
	v_fma_f32 v212, -v208, v211, v210
	v_fmac_f32_e32 v211, v212, v209
	v_fma_f32 v208, -v208, v211, v210
	v_div_fmas_f32 v208, v208, v209, v211
	v_div_fixup_f32 v220, v208, v203, 1.0
	v_div_scale_f32 v208, s[24:25], v204, v204, 1.0
	v_rcp_f32_e32 v209, v208
	s_nop 0
	v_fma_f32 v210, -v208, v209, 1.0
	v_fmac_f32_e32 v209, v210, v209
	v_div_scale_f32 v210, vcc, 1.0, v204, 1.0
	v_mul_f32_e32 v211, v210, v209
	v_fma_f32 v212, -v208, v211, v210
	v_fmac_f32_e32 v211, v212, v209
	v_fma_f32 v208, -v208, v211, v210
	v_div_fmas_f32 v208, v208, v209, v211
	v_div_fixup_f32 v222, v208, v204, 1.0
	v_div_scale_f32 v208, s[24:25], v205, v205, 1.0
	v_rcp_f32_e32 v209, v208
	s_nop 0
	v_fma_f32 v210, -v208, v209, 1.0
	v_fmac_f32_e32 v209, v210, v209
	v_div_scale_f32 v210, vcc, 1.0, v205, 1.0
	v_mul_f32_e32 v211, v210, v209
	v_fma_f32 v212, -v208, v211, v210
	v_fmac_f32_e32 v211, v212, v209
	v_fma_f32 v208, -v208, v211, v210
	v_div_fmas_f32 v208, v208, v209, v211
	v_div_fixup_f32 v224, v208, v205, 1.0
	v_div_scale_f32 v208, s[24:25], v206, v206, 1.0
	v_rcp_f32_e32 v209, v208
	s_nop 0
	v_fma_f32 v210, -v208, v209, 1.0
	v_fmac_f32_e32 v209, v210, v209
	v_div_scale_f32 v210, vcc, 1.0, v206, 1.0
	v_mul_f32_e32 v211, v210, v209
	v_fma_f32 v212, -v208, v211, v210
	v_fmac_f32_e32 v211, v212, v209
	v_fma_f32 v208, -v208, v211, v210
	v_div_fmas_f32 v208, v208, v209, v211
	v_div_fixup_f32 v226, v208, v206, 1.0
	v_div_scale_f32 v208, s[24:25], v207, v207, 1.0
	v_rcp_f32_e32 v209, v208
	s_nop 0
	v_fma_f32 v210, -v208, v209, 1.0
	v_fmac_f32_e32 v209, v210, v209
	v_div_scale_f32 v210, vcc, 1.0, v207, 1.0
	v_mul_f32_e32 v211, v210, v209
	v_fma_f32 v212, -v208, v211, v210
	v_fmac_f32_e32 v211, v212, v209
	v_fma_f32 v208, -v208, v211, v210
	v_div_fmas_f32 v208, v208, v209, v211
	v_div_fixup_f32 v228, v208, v207, 1.0
	s_waitcnt vmcnt(0)
; template <int EPI>
; __device__ __forceinline__ void gemm_acc_init(KP P, f32x4 (&acc)[2][2][4][2], int brow, int bcol, int wr, int wc, int fr_, int fq_, const float* sRu) {
;     ...
;       for (int m = 0; m < 4; ++m) {
;         __builtin_amdgcn_sched_barrier(0);
;         unsigned lr = ai * 128 + wr * 64 + m * 16 + fr;
;         unsigned o = lr * D + wc * 32 + fq * 4;
;         float sc = 1.f;
;         if (EPI == EPI_OUTPROJ) sc = 1.f / sRu[lr];
; #pragma unroll
;         for (int bj = 0; bj < 2; ++bj)
; #pragma unroll
;           for (int n = 0; n < 2; ++n) {
;             if (EPI == EPI_RES) acc[ai][bj][m][n] = bf4_to_f32(*(const uint2*)(xrb + o + bj * 128 + n * 16));
;             else acc[ai][bj][m][n] = *(const f32x4*)(xin + o + bj * 128 + n * 16) * sc;
;           }
; template <int EPI>
; __device__ __forceinline__ void gemm_phase(KP P, const bfu* __restrict__ A, const bfu* __restrict__ Bt, int K, int ntn, char* smem, const int wv) {
;     ...
;     sRu += 256;
;     gemm_acc_init<EPI>(P, acc, npm * 256, npn * 256, wr, wc, fr, fq, sRu);
;     ctile = ntile; cpm = npm; cpn = npn; cA = nA; cB = nB;
	v_pk_mul_f32 v[2:3], v[2:3], v[214:215] op_sel_hi:[1,0]
	v_pk_mul_f32 v[4:5], v[4:5], v[214:215] op_sel_hi:[1,0]
	v_pk_mul_f32 v[6:7], v[6:7], v[214:215] op_sel_hi:[1,0]
	v_pk_mul_f32 v[8:9], v[8:9], v[214:215] op_sel_hi:[1,0]
	v_pk_mul_f32 v[10:11], v[10:11], v[214:215] op_sel_hi:[1,0]
	v_pk_mul_f32 v[12:13], v[12:13], v[214:215] op_sel_hi:[1,0]
	v_pk_mul_f32 v[14:15], v[14:15], v[214:215] op_sel_hi:[1,0]
	v_pk_mul_f32 v[16:17], v[16:17], v[214:215] op_sel_hi:[1,0]
	v_pk_mul_f32 v[18:19], v[18:19], v[216:217] op_sel_hi:[1,0]
	v_pk_mul_f32 v[20:21], v[20:21], v[216:217] op_sel_hi:[1,0]
	v_pk_mul_f32 v[22:23], v[22:23], v[216:217] op_sel_hi:[1,0]
	v_pk_mul_f32 v[24:25], v[24:25], v[216:217] op_sel_hi:[1,0]
	v_pk_mul_f32 v[26:27], v[26:27], v[216:217] op_sel_hi:[1,0]
	v_pk_mul_f32 v[28:29], v[28:29], v[216:217] op_sel_hi:[1,0]
	v_pk_mul_f32 v[30:31], v[30:31], v[216:217] op_sel_hi:[1,0]
	v_pk_mul_f32 v[32:33], v[32:33], v[216:217] op_sel_hi:[1,0]
	v_pk_mul_f32 v[34:35], v[34:35], v[218:219] op_sel_hi:[1,0]
	v_pk_mul_f32 v[36:37], v[36:37], v[218:219] op_sel_hi:[1,0]
	v_pk_mul_f32 v[38:39], v[38:39], v[218:219] op_sel_hi:[1,0]
	v_pk_mul_f32 v[40:41], v[40:41], v[218:219] op_sel_hi:[1,0]
	v_pk_mul_f32 v[42:43], v[42:43], v[218:219] op_sel_hi:[1,0]
	v_pk_mul_f32 v[44:45], v[44:45], v[218:219] op_sel_hi:[1,0]
	v_pk_mul_f32 v[46:47], v[46:47], v[218:219] op_sel_hi:[1,0]
	v_pk_mul_f32 v[48:49], v[48:49], v[218:219] op_sel_hi:[1,0]
	v_pk_mul_f32 v[50:51], v[50:51], v[220:221] op_sel_hi:[1,0]
	v_pk_mul_f32 v[52:53], v[52:53], v[220:221] op_sel_hi:[1,0]
	v_pk_mul_f32 v[54:55], v[54:55], v[220:221] op_sel_hi:[1,0]
	v_pk_mul_f32 v[56:57], v[56:57], v[220:221] op_sel_hi:[1,0]
	v_pk_mul_f32 v[58:59], v[58:59], v[220:221] op_sel_hi:[1,0]
	v_pk_mul_f32 v[60:61], v[60:61], v[220:221] op_sel_hi:[1,0]
	v_pk_mul_f32 v[62:63], v[62:63], v[220:221] op_sel_hi:[1,0]
	v_pk_mul_f32 v[64:65], v[64:65], v[220:221] op_sel_hi:[1,0]
	v_pk_mul_f32 v[66:67], v[66:67], v[222:223] op_sel_hi:[1,0]
	v_pk_mul_f32 v[68:69], v[68:69], v[222:223] op_sel_hi:[1,0]
	v_pk_mul_f32 v[70:71], v[70:71], v[222:223] op_sel_hi:[1,0]
	v_pk_mul_f32 v[72:73], v[72:73], v[222:223] op_sel_hi:[1,0]
	v_pk_mul_f32 v[74:75], v[74:75], v[222:223] op_sel_hi:[1,0]
	v_pk_mul_f32 v[76:77], v[76:77], v[222:223] op_sel_hi:[1,0]
	v_pk_mul_f32 v[78:79], v[78:79], v[222:223] op_sel_hi:[1,0]
	v_pk_mul_f32 v[80:81], v[80:81], v[222:223] op_sel_hi:[1,0]
	v_pk_mul_f32 v[82:83], v[82:83], v[224:225] op_sel_hi:[1,0]
	v_pk_mul_f32 v[84:85], v[84:85], v[224:225] op_sel_hi:[1,0]
	v_pk_mul_f32 v[86:87], v[86:87], v[224:225] op_sel_hi:[1,0]
	v_pk_mul_f32 v[88:89], v[88:89], v[224:225] op_sel_hi:[1,0]
	v_pk_mul_f32 v[90:91], v[90:91], v[224:225] op_sel_hi:[1,0]
	v_pk_mul_f32 v[92:93], v[92:93], v[224:225] op_sel_hi:[1,0]
	v_pk_mul_f32 v[94:95], v[94:95], v[224:225] op_sel_hi:[1,0]
	v_pk_mul_f32 v[96:97], v[96:97], v[224:225] op_sel_hi:[1,0]
	v_pk_mul_f32 v[98:99], v[98:99], v[226:227] op_sel_hi:[1,0]
	v_pk_mul_f32 v[100:101], v[100:101], v[226:227] op_sel_hi:[1,0]
	v_pk_mul_f32 v[102:103], v[102:103], v[226:227] op_sel_hi:[1,0]
	v_pk_mul_f32 v[104:105], v[104:105], v[226:227] op_sel_hi:[1,0]
	v_pk_mul_f32 v[106:107], v[106:107], v[226:227] op_sel_hi:[1,0]
	v_pk_mul_f32 v[108:109], v[108:109], v[226:227] op_sel_hi:[1,0]
	v_pk_mul_f32 v[110:111], v[110:111], v[226:227] op_sel_hi:[1,0]
	v_pk_mul_f32 v[112:113], v[112:113], v[226:227] op_sel_hi:[1,0]
	v_pk_mul_f32 v[114:115], v[114:115], v[228:229] op_sel_hi:[1,0]
	v_pk_mul_f32 v[116:117], v[116:117], v[228:229] op_sel_hi:[1,0]
	v_pk_mul_f32 v[118:119], v[118:119], v[228:229] op_sel_hi:[1,0]
	v_pk_mul_f32 v[120:121], v[120:121], v[228:229] op_sel_hi:[1,0]
	v_pk_mul_f32 v[122:123], v[122:123], v[228:229] op_sel_hi:[1,0]
	v_pk_mul_f32 v[124:125], v[124:125], v[228:229] op_sel_hi:[1,0]
	v_pk_mul_f32 v[126:127], v[126:127], v[228:229] op_sel_hi:[1,0]
	v_pk_mul_f32 v[128:129], v[128:129], v[228:229] op_sel_hi:[1,0]
	s_mov_b64 s[20:21], 0
	s_mov_b32 s74, s5
	s_branch .LBB0_306

; __device__ __forceinline__ void phase_ssd(KP P, char* smem, const int wv) {
;     ...
;       {
;         const float dec = __expf(a63);
; #pragma unroll
;         for (int nt = 0; nt < 8; ++nt) hacc[nt] *= dec;
; #pragma unroll
;         for (int ks = 0; ks < 2; ++ks) {
;           const int j0 = ks * 32 + fqc * 8;
;           bf16x8 xr = lds_b128(xrow + j0);
;           f32x4 w0 = *(const f32x4*)(myW + j0), w1 = *(const f32x4*)(myW + j0 + 4);
;           u32x4 xu = __builtin_bit_cast(u32x4, xr);
;           u32x4 pk;
;           pk[0] = cvt_pk_bf16(__uint_as_float(xu[0] << 16) * w0[0], __uint_as_float(xu[0] & 0xffff0000u) * w0[1]);
;           pk[1] = cvt_pk_bf16(__uint_as_float(xu[1] << 16) * w0[2], __uint_as_float(xu[1] & 0xffff0000u) * w0[3]);
;           pk[2] = cvt_pk_bf16(__uint_as_float(xu[2] << 16) * w1[0], __uint_as_float(xu[2] & 0xffff0000u) * w1[1]);
;           pk[3] = cvt_pk_bf16(__uint_as_float(xu[3] << 16) * w1[2], __uint_as_float(xu[3] & 0xffff0000u) * w1[3]);
;           bf16x8 af = __builtin_bit_cast(bf16x8, pk);
; #pragma unroll
;           for (int nt = 0; nt < 8; ++nt) {
;             bf16x8 b = lds_b128(sBT + (nt * 16 + frc) * S_LDT + j0);
;             hacc[nt] = mfma16(af, b, hacc[nt]);
;           }
;         }
.LBB0_441:
	v_mul_f32_e32 v80, s49, v175
	v_exp_f32_e32 v80, v80
	v_lshlrev_b32_e32 v95, 1, v94
	v_lshl_add_u32 v94, v94, 2, s70
	v_add3_u32 v95, s64, v95, v97
	v_pk_mul_f32 v[30:31], v[30:31], v[80:81] op_sel_hi:[1,0]
	v_pk_mul_f32 v[28:29], v[28:29], v[80:81] op_sel_hi:[1,0]
	v_pk_mul_f32 v[34:35], v[34:35], v[80:81] op_sel_hi:[1,0]
	v_pk_mul_f32 v[32:33], v[32:33], v[80:81] op_sel_hi:[1,0]
	v_pk_mul_f32 v[22:23], v[22:23], v[80:81] op_sel_hi:[1,0]
	v_pk_mul_f32 v[20:21], v[20:21], v[80:81] op_sel_hi:[1,0]
	v_pk_mul_f32 v[26:27], v[26:27], v[80:81] op_sel_hi:[1,0]
	v_pk_mul_f32 v[24:25], v[24:25], v[80:81] op_sel_hi:[1,0]
	v_pk_mul_f32 v[14:15], v[14:15], v[80:81] op_sel_hi:[1,0]
	v_pk_mul_f32 v[12:13], v[12:13], v[80:81] op_sel_hi:[1,0]
	v_pk_mul_f32 v[18:19], v[18:19], v[80:81] op_sel_hi:[1,0]
	v_pk_mul_f32 v[16:17], v[16:17], v[80:81] op_sel_hi:[1,0]
	v_pk_mul_f32 v[6:7], v[6:7], v[80:81] op_sel_hi:[1,0]
	v_pk_mul_f32 v[4:5], v[4:5], v[80:81] op_sel_hi:[1,0]
	v_pk_mul_f32 v[10:11], v[10:11], v[80:81] op_sel_hi:[1,0]
	v_pk_mul_f32 v[8:9], v[8:9], v[80:81] op_sel_hi:[1,0]
	ds_read_b128 v[84:87], v94
	ds_read_b128 v[88:91], v94 offset:16
	ds_read_b128 v[104:107], v94 offset:128
	ds_read_b128 v[108:111], v94 offset:144
	ds_read_b128 v[156:159], v95 offset:34816
	ds_read_b128 v[160:163], v95 offset:37120
	ds_read_b128 v[208:211], v95 offset:39424
	ds_read_b128 v[212:215], v95 offset:41728
	ds_read_b128 v[216:219], v95 offset:44032
	ds_read_b128 v[220:223], v95 offset:46336
	ds_read_b128 v[224:227], v95 offset:48640
	ds_read_b128 v[236:239], v95 offset:50944
	s_waitcnt lgkmcnt(8)
	v_lshlrev_b32_e32 v96, 16, v228
	v_and_b32_e32 v97, 0xffff0000, v228
	v_mul_f32_e32 v96, v84, v96
	v_mul_f32_e32 v97, v85, v97
	v_cvt_pk_bf16_f32 v80, v96, v97
	v_lshlrev_b32_e32 v96, 16, v229
	v_and_b32_e32 v97, 0xffff0000, v229
	v_mul_f32_e32 v96, v86, v96
	v_mul_f32_e32 v97, v87, v97
	v_cvt_pk_bf16_f32 v81, v96, v97
	v_lshlrev_b32_e32 v96, 16, v230
	v_and_b32_e32 v97, 0xffff0000, v230
	v_mul_f32_e32 v96, v88, v96
	v_mul_f32_e32 v97, v89, v97
	v_cvt_pk_bf16_f32 v82, v96, v97
	v_lshlrev_b32_e32 v96, 16, v231
	v_and_b32_e32 v97, 0xffff0000, v231
	v_mul_f32_e32 v96, v90, v96
	v_mul_f32_e32 v97, v91, v97
	v_cvt_pk_bf16_f32 v83, v96, v97
	v_lshlrev_b32_e32 v96, 16, v232
	v_and_b32_e32 v97, 0xffff0000, v232
	v_mul_f32_e32 v96, v104, v96
	v_mul_f32_e32 v97, v105, v97
	v_cvt_pk_bf16_f32 v100, v96, v97
	v_lshlrev_b32_e32 v96, 16, v233
	v_and_b32_e32 v97, 0xffff0000, v233
	v_mul_f32_e32 v96, v106, v96
	v_mul_f32_e32 v97, v107, v97
	v_cvt_pk_bf16_f32 v101, v96, v97
	v_lshlrev_b32_e32 v96, 16, v234
	v_and_b32_e32 v97, 0xffff0000, v234
	v_mul_f32_e32 v96, v108, v96
	v_mul_f32_e32 v97, v109, v97
	v_cvt_pk_bf16_f32 v102, v96, v97
	v_lshlrev_b32_e32 v96, 16, v235
	v_and_b32_e32 v97, 0xffff0000, v235
	v_mul_f32_e32 v96, v110, v96
	v_mul_f32_e32 v97, v111, v97
	v_cvt_pk_bf16_f32 v103, v96, v97
	s_waitcnt lgkmcnt(7)
	v_mfma_f32_16x16x32_bf16 v[28:31], v[80:83], v[156:159], v[28:31]
	ds_read_b128 v[156:159], v95 offset:34880
	s_waitcnt lgkmcnt(7)
	v_mfma_f32_16x16x32_bf16 v[32:35], v[80:83], v[160:163], v[32:35]
	ds_read_b128 v[160:163], v95 offset:37184
	s_waitcnt lgkmcnt(7)
	v_mfma_f32_16x16x32_bf16 v[20:23], v[80:83], v[208:211], v[20:23]
	ds_read_b128 v[208:211], v95 offset:39488
	s_waitcnt lgkmcnt(7)
	v_mfma_f32_16x16x32_bf16 v[24:27], v[80:83], v[212:215], v[24:27]
	ds_read_b128 v[212:215], v95 offset:41792
	s_waitcnt lgkmcnt(7)
	v_mfma_f32_16x16x32_bf16 v[12:15], v[80:83], v[216:219], v[12:15]
	ds_read_b128 v[216:219], v95 offset:44096
	s_waitcnt lgkmcnt(7)
	v_mfma_f32_16x16x32_bf16 v[16:19], v[80:83], v[220:223], v[16:19]
	ds_read_b128 v[220:223], v95 offset:46400
	s_waitcnt lgkmcnt(7)
	v_mfma_f32_16x16x32_bf16 v[4:7], v[80:83], v[224:227], v[4:7]
	ds_read_b128 v[224:227], v95 offset:48704
	s_waitcnt lgkmcnt(7)
	v_mfma_f32_16x16x32_bf16 v[8:11], v[80:83], v[236:239], v[8:11]
	ds_read_b128 v[236:239], v95 offset:51008
	s_waitcnt lgkmcnt(7)
	v_mfma_f32_16x16x32_bf16 v[28:31], v[100:103], v[156:159], v[28:31]
	s_waitcnt lgkmcnt(6)
	v_mfma_f32_16x16x32_bf16 v[32:35], v[100:103], v[160:163], v[32:35]
	s_waitcnt lgkmcnt(5)
	v_mfma_f32_16x16x32_bf16 v[20:23], v[100:103], v[208:211], v[20:23]
	s_waitcnt lgkmcnt(4)
; __device__ __forceinline__ void phase_ssd(KP P, char* smem, const int wv) {
;     ...
;           for (int nt = 0; nt < 8; ++nt) {
;             bf16x8 b = lds_b128(sBT + (nt * 16 + frc) * S_LDT + j0);
;             hacc[nt] = mfma16(af, b, hacc[nt]);
;           }
;         }
; #pragma unroll
;         for (int nt = 0; nt < 8; ++nt)
; #pragma unroll
;           for (int j = 0; j < 4; ++j) myH[(fqc * 4 + j) * S_LDB + nt * 16 + frc] = f2bf(hacc[nt][j]);
;       }
;       lds_barrier();
;       if (tid < 64) {
;         float sm = 0.f;
; #pragma unroll
;         for (int ww = 0; ww < 8; ++ww) sm += sSq[ww * 64 + tid];
;         ssqp[(size_t)(r0 + tid) * 16 + g * 4 + hp] = sm;
;       }
	v_mfma_f32_16x16x32_bf16 v[24:27], v[100:103], v[212:215], v[24:27]
	s_waitcnt lgkmcnt(3)
	v_mfma_f32_16x16x32_bf16 v[12:15], v[100:103], v[216:219], v[12:15]
	s_waitcnt lgkmcnt(2)
	v_mfma_f32_16x16x32_bf16 v[16:19], v[100:103], v[220:223], v[16:19]
	s_waitcnt lgkmcnt(1)
	v_mfma_f32_16x16x32_bf16 v[4:7], v[100:103], v[224:227], v[4:7]
	s_waitcnt lgkmcnt(0)
	v_mfma_f32_16x16x32_bf16 v[8:11], v[100:103], v[236:239], v[8:11]
	v_bfe_u32 v80, v28, 16, 1
	v_lshlrev_b32_e32 v81, 1, v92
	v_add3_u32 v80, v28, v80, s96
	v_add3_u32 v0, s9, v81, v0
	ds_write_b16_d16_hi v0, v80
	v_bfe_u32 v80, v29, 16, 1
	v_add3_u32 v80, v29, v80, s96
	ds_write_b16_d16_hi v0, v80 offset:272
	v_bfe_u32 v80, v30, 16, 1
	v_add3_u32 v80, v30, v80, s96
	ds_write_b16_d16_hi v0, v80 offset:544
	v_bfe_u32 v80, v31, 16, 1
	v_add3_u32 v80, v31, v80, s96
	ds_write_b16_d16_hi v0, v80 offset:816
	v_bfe_u32 v80, v32, 16, 1
	v_add3_u32 v80, v32, v80, s96
	ds_write_b16_d16_hi v0, v80 offset:32
	v_bfe_u32 v80, v33, 16, 1
	v_add3_u32 v80, v33, v80, s96
	ds_write_b16_d16_hi v0, v80 offset:304
	v_bfe_u32 v80, v34, 16, 1
	v_add3_u32 v80, v34, v80, s96
	ds_write_b16_d16_hi v0, v80 offset:576
	v_bfe_u32 v80, v35, 16, 1
	v_add3_u32 v80, v35, v80, s96
	ds_write_b16_d16_hi v0, v80 offset:848
	v_bfe_u32 v80, v20, 16, 1
	v_add3_u32 v80, v20, v80, s96
	ds_write_b16_d16_hi v0, v80 offset:64
	v_bfe_u32 v80, v21, 16, 1
	v_add3_u32 v80, v21, v80, s96
	ds_write_b16_d16_hi v0, v80 offset:336
	v_bfe_u32 v80, v22, 16, 1
	v_add3_u32 v80, v22, v80, s96
	ds_write_b16_d16_hi v0, v80 offset:608
	v_bfe_u32 v80, v23, 16, 1
	v_add3_u32 v80, v23, v80, s96
	ds_write_b16_d16_hi v0, v80 offset:880
	v_bfe_u32 v80, v24, 16, 1
	v_add3_u32 v80, v24, v80, s96
	ds_write_b16_d16_hi v0, v80 offset:96
	v_bfe_u32 v80, v25, 16, 1
	v_add3_u32 v80, v25, v80, s96
	ds_write_b16_d16_hi v0, v80 offset:368
	v_bfe_u32 v80, v26, 16, 1
	v_add3_u32 v80, v26, v80, s96
	ds_write_b16_d16_hi v0, v80 offset:640
	v_bfe_u32 v80, v27, 16, 1
	v_add3_u32 v80, v27, v80, s96
	ds_write_b16_d16_hi v0, v80 offset:912
	v_bfe_u32 v80, v12, 16, 1
	v_add3_u32 v80, v12, v80, s96
	ds_write_b16_d16_hi v0, v80 offset:128
	v_bfe_u32 v80, v13, 16, 1
	v_add3_u32 v80, v13, v80, s96
	ds_write_b16_d16_hi v0, v80 offset:400
	v_bfe_u32 v80, v14, 16, 1
	v_add3_u32 v80, v14, v80, s96
	ds_write_b16_d16_hi v0, v80 offset:672
	v_bfe_u32 v80, v15, 16, 1
	v_add3_u32 v80, v15, v80, s96
	ds_write_b16_d16_hi v0, v80 offset:944
	v_bfe_u32 v80, v16, 16, 1
	v_add3_u32 v80, v16, v80, s96
	ds_write_b16_d16_hi v0, v80 offset:160
	v_bfe_u32 v80, v17, 16, 1
	v_add3_u32 v80, v17, v80, s96
	ds_write_b16_d16_hi v0, v80 offset:432
	v_bfe_u32 v80, v18, 16, 1
	v_add3_u32 v80, v18, v80, s96
	ds_write_b16_d16_hi v0, v80 offset:704
	v_bfe_u32 v80, v19, 16, 1
	v_add3_u32 v80, v19, v80, s96
	ds_write_b16_d16_hi v0, v80 offset:976
	v_bfe_u32 v80, v4, 16, 1
	v_add3_u32 v80, v4, v80, s96
	ds_write_b16_d16_hi v0, v80 offset:192
	v_bfe_u32 v80, v5, 16, 1
	v_add3_u32 v80, v5, v80, s96
	ds_write_b16_d16_hi v0, v80 offset:464
	v_bfe_u32 v80, v6, 16, 1
	v_add3_u32 v80, v6, v80, s96
	ds_write_b16_d16_hi v0, v80 offset:736
	v_bfe_u32 v80, v7, 16, 1
	v_add3_u32 v80, v7, v80, s96
	ds_write_b16_d16_hi v0, v80 offset:1008
	v_bfe_u32 v80, v8, 16, 1
	v_add3_u32 v80, v8, v80, s96
	ds_write_b16_d16_hi v0, v80 offset:224
	v_bfe_u32 v80, v9, 16, 1
	v_add3_u32 v80, v9, v80, s96
	ds_write_b16_d16_hi v0, v80 offset:496
	v_bfe_u32 v80, v10, 16, 1
	v_add3_u32 v80, v10, v80, s96
	ds_write_b16_d16_hi v0, v80 offset:768
	v_bfe_u32 v80, v11, 16, 1
	v_add3_u32 v80, v11, v80, s96
	ds_write_b16_d16_hi v0, v80 offset:1040
	s_waitcnt lgkmcnt(0)
	s_barrier
	s_and_saveexec_b64 s[34:35], s[14:15]
	s_cbranch_execz .LBB0_414
	ds_read2st64_b32 v[80:81], v204 offset1:1
	ds_read2st64_b32 v[82:83], v204 offset0:2 offset1:3
	ds_read2st64_b32 v[84:85], v204 offset0:4 offset1:5
	ds_read2st64_b32 v[86:87], v204 offset0:6 offset1:7
	v_add_u32_e32 v88, s48, v113
	v_ashrrev_i32_e32 v89, 31, v88
	v_lshlrev_b64 v[88:89], 6, v[88:89]
	v_lshl_add_u64 v[88:89], s[80:81], 0, v[88:89]
	s_waitcnt lgkmcnt(0)
	v_add_f32_e32 v0, 0, v80
	v_add_f32_e32 v0, v0, v81
	v_add_f32_e32 v0, v0, v82
	v_add_f32_e32 v0, v0, v83
	v_add_f32_e32 v0, v0, v84
	v_add_f32_e32 v0, v0, v85
	v_add_f32_e32 v0, v0, v86
	v_add_f32_e32 v0, v0, v87
	global_store_dword v[88:89], v0, off
	s_branch .LBB0_414
